# context half-tile residual epilogues batched (32 loads in flight); merge_half gate GEMM issues next-tile loads right after its LDS stores
# speedup vs baseline: 1.1055x; 1.0059x over previous
; #define MFMA32(a, b, c) __builtin_amdgcn_mfma_f32_32x32x16_bf16((a), (b), (c), 0, 0, 0)
; DI int tidx() { int t = __builtin_amdgcn_workitem_id_x(); asm volatile("" : "+v"(t)); return t; }
; #define GEMM_LOADG(kk) { const int ka_ = amode ? (((kk) >> 6) * 96) : (kk); \
;     _Pragma("unroll") for (int i = 0; i < 4; ++i) ra[i] = *(const u32x4*)(A + (size_t)(lr + 32 * i) * lda + ka_ + lk); \
;     _Pragma("unroll") for (int i = 0; i < 2 * NT; ++i) rb[i] = *(const u32x4*)(Bt + (size_t)(lr + 32 * i) * ldb + (kk) + lk); }
; #define GEMM_STORES(buf) { u16* As_ = S + (buf) * TILE; u16* Bs_ = As_ + 128 * LS; \
;     _Pragma("unroll") for (int i = 0; i < 4; ++i) *(u32x4*)(As_ + (lr + 32 * i) * LS + lk) = ra[i]; \
;     _Pragma("unroll") for (int i = 0; i < 2 * NT; ++i) *(u32x4*)(Bs_ + (lr + 32 * i) * LS + lk) = rb[i]; }
; template <int NT>
; DI void gemm_main_np(f32x16 (&acc)[2][NT], const u16* __restrict__ A, int lda, int amode, const u16* __restrict__ Bt,
;                   int ldb, int K, char* smem) {
;   constexpr int LS = 72;
;   constexpr int TILE = (128 + 64 * NT) * LS;
;   u16* S = (u16*)smem;
;   const int tid = tidx(), lane = tid & 63, w = tid >> 6, wm = w >> 1, wn = w & 1;
;   const int l31 = lane & 31, hh = lane >> 5;
;   const int lr = tid >> 3, lk = (tid & 7) * 8;
;   u32x4 ra[4], rb[2 * NT];
;     ...
;   GEMM_LOADG(0)
;   __syncthreads();
;   GEMM_STORES(0)
;   if (K > 64) GEMM_LOADG(64)
;   __syncthreads();
;   for (int k0 = 0; k0 < K; k0 += 64) {
;     const int cur = (k0 >> 6) & 1;
;     if (k0 + 64 < K) {
;       GEMM_STORES(cur ^ 1)
;       if (k0 + 128 < K) GEMM_LOADG(k0 + 128)
;     }
;     const u16* As = S + cur * TILE;
;     const u16* Bs = As + 128 * LS;
; #pragma unroll
;     for (int s = 0; s < 4; ++s) {
;       bf16x8 a[2], b[NT];
; #pragma unroll
;       for (int i = 0; i < 2; ++i) a[i] = *(const bf16x8*)(As + (wm * 64 + i * 32 + l31) * LS + s * 16 + hh * 8);
; #pragma unroll
;       for (int j = 0; j < NT; ++j) b[j] = *(const bf16x8*)(Bs + (wn * 32 * NT + j * 32 + l31) * LS + s * 16 + hh * 8);
; #pragma unroll
;       for (int i = 0; i < 2; ++i)
; #pragma unroll
;         for (int j = 0; j < NT; ++j) acc[i][j] = MFMA32(a[i], b[j], acc[i][j]);
;     }
;     __syncthreads();
.LBB0_1716:
	v_mov_b32_e32 v48, v0
	s_mov_b64 s[2:3], 0x10000
	v_ashrrev_i32_e32 v34, 3, v48
	v_lshlrev_b32_e32 v2, 4, v48
	v_and_b32_e32 v198, 0x70, v2
	v_ashrrev_i32_e32 v35, 31, v34
	v_lshl_add_u64 v[2:3], s[8:9], 0, v[198:199]
	v_lshlrev_b64 v[18:19], 11, v[34:35]
	v_lshl_add_u64 v[36:37], v[2:3], 0, v[18:19]
	v_lshl_add_u64 v[38:39], v[36:37], 0, s[2:3]
	s_mov_b32 s2, 0x10000
	v_add_co_u32_e32 v6, vcc, s2, v36
	s_mov_b64 s[2:3], 0x20000
	s_nop 0
	v_addc_co_u32_e32 v7, vcc, 0, v37, vcc
	v_lshl_add_u64 v[40:41], v[36:37], 0, s[2:3]
	s_mov_b32 s2, 0x20000
	v_add_co_u32_e32 v10, vcc, s2, v36
	s_mov_b64 s[2:3], 0x30000
	s_nop 0
	v_addc_co_u32_e32 v11, vcc, 0, v37, vcc
	v_lshl_add_u64 v[42:43], v[36:37], 0, s[2:3]
	s_mov_b32 s2, 0x30000
	v_add_co_u32_e32 v14, vcc, s2, v36
	v_and_b32_e32 v20, 7, v48
	s_add_u32 s2, s6, s26
	v_lshl_or_b32 v18, v20, 4, v18
	s_addc_u32 s3, s7, s27
	v_addc_co_u32_e32 v15, vcc, 0, v37, vcc
	v_lshl_add_u64 v[18:19], s[2:3], 0, v[18:19]
	s_mov_b32 s2, 0xd7d0000
	v_add_co_u32_e32 v44, vcc, s2, v18
	s_mov_b32 s2, 0xd7e0000
	s_nop 0
	v_addc_co_u32_e32 v45, vcc, 0, v19, vcc
	v_add_co_u32_e32 v46, vcc, s2, v18
	global_load_dwordx4 v[2:5], v[36:37], off
	s_nop 0
	global_load_dwordx4 v[6:9], v[6:7], off
	s_nop 0
	global_load_dwordx4 v[10:13], v[10:11], off
	s_nop 0
	global_load_dwordx4 v[14:17], v[14:15], off
	v_addc_co_u32_e32 v47, vcc, 0, v19, vcc
	global_load_dwordx4 v[18:21], v[44:45], off
	global_load_dwordx4 v[22:25], v[46:47], off
	s_waitcnt vmcnt(63) expcnt(7) lgkmcnt(15)
	s_barrier
	global_load_dwordx4 v[26:29], v[36:37], off offset:128
	global_load_dwordx4 v[30:33], v[38:39], off offset:128
	global_load_dwordx4 v[50:53], v[40:41], off offset:128
	global_load_dwordx4 v[54:57], v[42:43], off offset:128
	global_load_dwordx4 v[58:61], v[44:45], off offset:128
	global_load_dwordx4 v[62:65], v[46:47], off offset:128
	v_and_b32_e32 v67, 31, v48
	v_lshrrev_b32_e32 v68, 1, v48
	v_and_or_b32 v35, v68, s31, v67
	v_and_b32_e32 v66, 16, v68
	v_mad_u64_u32 v[48:49], s[2:3], v34, s60, v[198:199]
	v_mad_u64_u32 v[34:35], s[2:3], v35, s60, v[66:67]
	s_cmp_lt_i32 s29, 1
	s_waitcnt vmcnt(11)
	ds_write_b128 v48, v[2:5]
	s_waitcnt vmcnt(10)
	ds_write_b128 v48, v[6:9] offset:4608
	s_waitcnt vmcnt(9)
	ds_write_b128 v48, v[10:13] offset:9216
	s_waitcnt vmcnt(8)
	ds_write_b128 v48, v[14:17] offset:13824
	s_waitcnt vmcnt(7)
	ds_write_b128 v48, v[18:21] offset:18432
	s_waitcnt vmcnt(6)
	ds_write_b128 v48, v[22:25] offset:23040
	s_waitcnt lgkmcnt(0)
	s_barrier
	s_waitcnt vmcnt(5)
	ds_write_b128 v48, v[26:29] offset:27648
	s_waitcnt vmcnt(4)
	ds_write_b128 v48, v[30:33] offset:32256
	s_waitcnt vmcnt(3)
	ds_write_b128 v48, v[50:53] offset:36864
	s_waitcnt vmcnt(2)
	ds_write_b128 v48, v[54:57] offset:41472
	s_waitcnt vmcnt(1)
	ds_write_b128 v48, v[58:61] offset:46080
	s_waitcnt vmcnt(0)
	ds_write_b128 v48, v[62:65] offset:50688
	ds_read_b128 v[2:5], v34
	v_and_or_b32 v6, v68, 32, v67
	v_mad_u32_u24 v35, v6, s60, v66
	ds_read_b128 v[6:9], v35 offset:18432
	ds_read_b128 v[50:53], v34 offset:32
	ds_read_b128 v[54:57], v35 offset:18464
	s_waitcnt lgkmcnt(2)
	v_mfma_f32_32x32x16_bf16 v[18:33], v[2:5], v[6:9], 0
	ds_read_b128 v[2:5], v34 offset:4608
	ds_read_b128 v[58:61], v34 offset:4640
	s_waitcnt lgkmcnt(1)
	v_mfma_f32_32x32x16_bf16 v[2:17], v[2:5], v[6:9], 0
	v_mfma_f32_32x32x16_bf16 v[18:33], v[50:53], v[54:57], v[18:33]
	s_waitcnt lgkmcnt(0)
	v_mfma_f32_32x32x16_bf16 v[2:17], v[58:61], v[54:57], v[2:17]
	ds_read_b128 v[50:53], v34 offset:64
	ds_read_b128 v[54:57], v35 offset:18496
	ds_read_b128 v[58:61], v34 offset:96
	ds_read_b128 v[62:65], v35 offset:18528
	s_waitcnt lgkmcnt(2)
	v_mfma_f32_32x32x16_bf16 v[18:33], v[50:53], v[54:57], v[18:33]
	ds_read_b128 v[50:53], v34 offset:4672
	ds_read_b128 v[66:69], v34 offset:4704
	s_waitcnt lgkmcnt(1)
	v_mfma_f32_32x32x16_bf16 v[2:17], v[50:53], v[54:57], v[2:17]
	global_load_dwordx4 v[50:53], v[36:37], off offset:256
	global_load_dwordx4 v[54:57], v[38:39], off offset:256
	global_load_dwordx4 v[70:73], v[40:41], off offset:256
	global_load_dwordx4 v[74:77], v[42:43], off offset:256
	v_mfma_f32_32x32x16_bf16 v[18:33], v[58:61], v[62:65], v[18:33]
	global_load_dwordx4 v[58:61], v[44:45], off offset:256
	global_load_dwordx4 v[78:81], v[46:47], off offset:256
	s_waitcnt lgkmcnt(0)
	s_barrier
	s_waitcnt vmcnt(5)
	ds_write_b128 v48, v[50:53]
	s_waitcnt vmcnt(4)
	ds_write_b128 v48, v[54:57] offset:4608
	s_waitcnt vmcnt(3)
	ds_write_b128 v48, v[70:73] offset:9216
	s_waitcnt vmcnt(2)
	ds_write_b128 v48, v[74:77] offset:13824
	s_waitcnt vmcnt(1)
	ds_write_b128 v48, v[58:61] offset:18432
	s_waitcnt vmcnt(0)
	ds_write_b128 v48, v[78:81] offset:23040
	global_load_dwordx4 v[142:145], v[36:37], off offset:384
	global_load_dwordx4 v[146:149], v[38:39], off offset:384
	global_load_dwordx4 v[150:153], v[40:41], off offset:384
	global_load_dwordx4 v[154:157], v[42:43], off offset:384
	global_load_dwordx4 v[158:161], v[44:45], off offset:384
	global_load_dwordx4 v[162:165], v[46:47], off offset:384
	v_mfma_f32_32x32x16_bf16 v[2:17], v[66:69], v[62:65], v[2:17]
	ds_read_b128 v[50:53], v34 offset:27648
	ds_read_b128 v[54:57], v35 offset:46080
	ds_read_b128 v[58:61], v34 offset:27680
	ds_read_b128 v[62:65], v35 offset:46112
	s_waitcnt lgkmcnt(2)
	v_mfma_f32_32x32x16_bf16 v[18:33], v[50:53], v[54:57], v[18:33]
	ds_read_b128 v[50:53], v34 offset:32256
	ds_read_b128 v[66:69], v34 offset:32288
	s_waitcnt lgkmcnt(1)
	v_mfma_f32_32x32x16_bf16 v[2:17], v[50:53], v[54:57], v[2:17]
	v_mfma_f32_32x32x16_bf16 v[18:33], v[58:61], v[62:65], v[18:33]
	s_waitcnt lgkmcnt(0)
	v_mfma_f32_32x32x16_bf16 v[2:17], v[66:69], v[62:65], v[2:17]
	ds_read_b128 v[50:53], v34 offset:27712
	ds_read_b128 v[54:57], v35 offset:46144
	ds_read_b128 v[58:61], v34 offset:27744
	ds_read_b128 v[62:65], v35 offset:46176
	s_waitcnt lgkmcnt(2)
	v_mfma_f32_32x32x16_bf16 v[18:33], v[50:53], v[54:57], v[18:33]
	ds_read_b128 v[50:53], v34 offset:32320
	ds_read_b128 v[82:85], v34 offset:32352
	s_waitcnt lgkmcnt(1)
	v_mfma_f32_32x32x16_bf16 v[2:17], v[50:53], v[54:57], v[2:17]
	s_waitcnt lgkmcnt(0)
	s_barrier
; #define MFMA32(a, b, c) __builtin_amdgcn_mfma_f32_32x32x16_bf16((a), (b), (c), 0, 0, 0)
; #define GEMM_LOADG(kk) { const int ka_ = amode ? (((kk) >> 6) * 96) : (kk); \
;     _Pragma("unroll") for (int i = 0; i < 4; ++i) ra[i] = *(const u32x4*)(A + (size_t)(lr + 32 * i) * lda + ka_ + lk); \
;     _Pragma("unroll") for (int i = 0; i < 2 * NT; ++i) rb[i] = *(const u32x4*)(Bt + (size_t)(lr + 32 * i) * ldb + (kk) + lk); }
; #define GEMM_STORES(buf) { u16* As_ = S + (buf) * TILE; u16* Bs_ = As_ + 128 * LS; \
;     _Pragma("unroll") for (int i = 0; i < 4; ++i) *(u32x4*)(As_ + (lr + 32 * i) * LS + lk) = ra[i]; \
;     _Pragma("unroll") for (int i = 0; i < 2 * NT; ++i) *(u32x4*)(Bs_ + (lr + 32 * i) * LS + lk) = rb[i]; }
; template <int NT>
; DI void gemm_main_np(f32x16 (&acc)[2][NT], const u16* __restrict__ A, int lda, int amode, const u16* __restrict__ Bt,
;                   int ldb, int K, char* smem) {
;     ...
;   GEMM_LOADG(0)
;   __syncthreads();
;   GEMM_STORES(0)
;   if (K > 64) GEMM_LOADG(64)
;   __syncthreads();
;   for (int k0 = 0; k0 < K; k0 += 64) {
;     const int cur = (k0 >> 6) & 1;
;     if (k0 + 64 < K) {
;       GEMM_STORES(cur ^ 1)
;       if (k0 + 128 < K) GEMM_LOADG(k0 + 128)
;     }
;     const u16* As = S + cur * TILE;
;     const u16* Bs = As + 128 * LS;
; #pragma unroll
;     for (int s = 0; s < 4; ++s) {
;       bf16x8 a[2], b[NT];
; #pragma unroll
;       for (int i = 0; i < 2; ++i) a[i] = *(const bf16x8*)(As + (wm * 64 + i * 32 + l31) * LS + s * 16 + hh * 8);
; #pragma unroll
;       for (int j = 0; j < NT; ++j) b[j] = *(const bf16x8*)(Bs + (wn * 32 * NT + j * 32 + l31) * LS + s * 16 + hh * 8);
; #pragma unroll
;       for (int i = 0; i < 2; ++i)
; #pragma unroll
;         for (int j = 0; j < NT; ++j) acc[i][j] = MFMA32(a[i], b[j], acc[i][j]);
;     }
;     __syncthreads();
	s_waitcnt vmcnt(5)
	ds_write_b128 v48, v[142:145] offset:27648
	s_waitcnt vmcnt(4)
	ds_write_b128 v48, v[146:149] offset:32256
	s_waitcnt vmcnt(3)
	ds_write_b128 v48, v[150:153] offset:36864
	s_waitcnt vmcnt(2)
	ds_write_b128 v48, v[154:157] offset:41472
	s_waitcnt vmcnt(1)
	ds_write_b128 v48, v[158:161] offset:46080
	s_waitcnt vmcnt(0)
	ds_write_b128 v48, v[162:165] offset:50688
	global_load_dwordx4 v[142:145], v[36:37], off offset:512
	global_load_dwordx4 v[146:149], v[38:39], off offset:512
	global_load_dwordx4 v[150:153], v[40:41], off offset:512
	global_load_dwordx4 v[154:157], v[42:43], off offset:512
	global_load_dwordx4 v[158:161], v[44:45], off offset:512
	global_load_dwordx4 v[162:165], v[46:47], off offset:512
	v_mfma_f32_32x32x16_bf16 v[18:33], v[58:61], v[62:65], v[18:33]
	v_mfma_f32_32x32x16_bf16 v[2:17], v[82:85], v[62:65], v[2:17]
	ds_read_b128 v[50:53], v34
	ds_read_b128 v[54:57], v35 offset:18432
	ds_read_b128 v[58:61], v34 offset:32
	ds_read_b128 v[62:65], v35 offset:18464
	s_waitcnt lgkmcnt(2)
	v_mfma_f32_32x32x16_bf16 v[18:33], v[50:53], v[54:57], v[18:33]
	ds_read_b128 v[50:53], v34 offset:4608
	ds_read_b128 v[66:69], v34 offset:4640
	s_waitcnt lgkmcnt(1)
	v_mfma_f32_32x32x16_bf16 v[2:17], v[50:53], v[54:57], v[2:17]
	v_mfma_f32_32x32x16_bf16 v[18:33], v[58:61], v[62:65], v[18:33]
	s_waitcnt lgkmcnt(0)
	v_mfma_f32_32x32x16_bf16 v[2:17], v[66:69], v[62:65], v[2:17]
	ds_read_b128 v[50:53], v34 offset:64
	ds_read_b128 v[54:57], v35 offset:18496
	ds_read_b128 v[58:61], v34 offset:96
	ds_read_b128 v[62:65], v35 offset:18528
	s_waitcnt lgkmcnt(2)
	v_mfma_f32_32x32x16_bf16 v[18:33], v[50:53], v[54:57], v[18:33]
	ds_read_b128 v[50:53], v34 offset:4672
	ds_read_b128 v[66:69], v34 offset:4704
	s_waitcnt lgkmcnt(1)
	v_mfma_f32_32x32x16_bf16 v[2:17], v[50:53], v[54:57], v[2:17]
	v_mfma_f32_32x32x16_bf16 v[18:33], v[58:61], v[62:65], v[18:33]
	s_waitcnt lgkmcnt(0)
	s_barrier
	s_waitcnt vmcnt(5)
	ds_write_b128 v48, v[142:145]
	s_waitcnt vmcnt(4)
	ds_write_b128 v48, v[146:149] offset:4608
	s_waitcnt vmcnt(3)
	ds_write_b128 v48, v[150:153] offset:9216
	s_waitcnt vmcnt(2)
	ds_write_b128 v48, v[154:157] offset:13824
	s_waitcnt vmcnt(1)
	ds_write_b128 v48, v[158:161] offset:18432
	s_waitcnt vmcnt(0)
	ds_write_b128 v48, v[162:165] offset:23040
	global_load_dwordx4 v[142:145], v[36:37], off offset:640
	global_load_dwordx4 v[146:149], v[38:39], off offset:640
	global_load_dwordx4 v[150:153], v[40:41], off offset:640
	global_load_dwordx4 v[154:157], v[42:43], off offset:640
	global_load_dwordx4 v[158:161], v[44:45], off offset:640
	global_load_dwordx4 v[162:165], v[46:47], off offset:640
	v_mfma_f32_32x32x16_bf16 v[2:17], v[66:69], v[62:65], v[2:17]
	ds_read_b128 v[50:53], v34 offset:27648
	ds_read_b128 v[54:57], v35 offset:46080
	ds_read_b128 v[58:61], v34 offset:27680
	ds_read_b128 v[62:65], v35 offset:46112
	s_waitcnt lgkmcnt(2)
	v_mfma_f32_32x32x16_bf16 v[18:33], v[50:53], v[54:57], v[18:33]
	ds_read_b128 v[50:53], v34 offset:32256
	ds_read_b128 v[66:69], v34 offset:32288
	s_waitcnt lgkmcnt(1)
	v_mfma_f32_32x32x16_bf16 v[2:17], v[50:53], v[54:57], v[2:17]
	v_mfma_f32_32x32x16_bf16 v[18:33], v[58:61], v[62:65], v[18:33]
	s_waitcnt lgkmcnt(0)
	v_mfma_f32_32x32x16_bf16 v[2:17], v[66:69], v[62:65], v[2:17]
	ds_read_b128 v[50:53], v34 offset:27712
	ds_read_b128 v[54:57], v35 offset:46144
	ds_read_b128 v[58:61], v34 offset:27744
	ds_read_b128 v[62:65], v35 offset:46176
	s_waitcnt lgkmcnt(2)
	v_mfma_f32_32x32x16_bf16 v[18:33], v[50:53], v[54:57], v[18:33]
	ds_read_b128 v[50:53], v34 offset:32320
	ds_read_b128 v[82:85], v34 offset:32352
	s_waitcnt lgkmcnt(1)
	v_mfma_f32_32x32x16_bf16 v[2:17], v[50:53], v[54:57], v[2:17]
	s_waitcnt lgkmcnt(0)
	s_barrier
	s_waitcnt vmcnt(5)
	ds_write_b128 v48, v[142:145] offset:27648
	s_waitcnt vmcnt(4)
	ds_write_b128 v48, v[146:149] offset:32256
	s_waitcnt vmcnt(3)
	ds_write_b128 v48, v[150:153] offset:36864
	s_waitcnt vmcnt(2)
	ds_write_b128 v48, v[154:157] offset:41472
	s_waitcnt vmcnt(1)
	ds_write_b128 v48, v[158:161] offset:46080
	s_waitcnt vmcnt(0)
	ds_write_b128 v48, v[162:165] offset:50688
	global_load_dwordx4 v[142:145], v[36:37], off offset:768
	global_load_dwordx4 v[146:149], v[38:39], off offset:768
	global_load_dwordx4 v[150:153], v[40:41], off offset:768
	global_load_dwordx4 v[154:157], v[42:43], off offset:768
	global_load_dwordx4 v[158:161], v[44:45], off offset:768
	global_load_dwordx4 v[162:165], v[46:47], off offset:768
	v_mfma_f32_32x32x16_bf16 v[18:33], v[58:61], v[62:65], v[18:33]
	v_mfma_f32_32x32x16_bf16 v[2:17], v[82:85], v[62:65], v[2:17]
	ds_read_b128 v[50:53], v34
	ds_read_b128 v[54:57], v35 offset:18432
	ds_read_b128 v[58:61], v34 offset:32
	ds_read_b128 v[62:65], v35 offset:18464
	s_waitcnt lgkmcnt(2)
	v_mfma_f32_32x32x16_bf16 v[18:33], v[50:53], v[54:57], v[18:33]
	ds_read_b128 v[50:53], v34 offset:4608
	ds_read_b128 v[66:69], v34 offset:4640
	s_waitcnt lgkmcnt(1)
	v_mfma_f32_32x32x16_bf16 v[2:17], v[50:53], v[54:57], v[2:17]
	v_mfma_f32_32x32x16_bf16 v[18:33], v[58:61], v[62:65], v[18:33]
	s_waitcnt lgkmcnt(0)
	v_mfma_f32_32x32x16_bf16 v[2:17], v[66:69], v[62:65], v[2:17]
	ds_read_b128 v[50:53], v34 offset:64
	ds_read_b128 v[54:57], v35 offset:18496
	ds_read_b128 v[58:61], v34 offset:96
	ds_read_b128 v[62:65], v35 offset:18528
	s_waitcnt lgkmcnt(2)
	v_mfma_f32_32x32x16_bf16 v[18:33], v[50:53], v[54:57], v[18:33]
	ds_read_b128 v[50:53], v34 offset:4672
	ds_read_b128 v[66:69], v34 offset:4704
	s_waitcnt lgkmcnt(1)
	v_mfma_f32_32x32x16_bf16 v[2:17], v[50:53], v[54:57], v[2:17]
	v_mfma_f32_32x32x16_bf16 v[18:33], v[58:61], v[62:65], v[18:33]
	s_waitcnt lgkmcnt(0)
	s_barrier
; #define MFMA32(a, b, c) __builtin_amdgcn_mfma_f32_32x32x16_bf16((a), (b), (c), 0, 0, 0)
; #define GEMM_LOADG(kk) { const int ka_ = amode ? (((kk) >> 6) * 96) : (kk); \
;     _Pragma("unroll") for (int i = 0; i < 4; ++i) ra[i] = *(const u32x4*)(A + (size_t)(lr + 32 * i) * lda + ka_ + lk); \
;     _Pragma("unroll") for (int i = 0; i < 2 * NT; ++i) rb[i] = *(const u32x4*)(Bt + (size_t)(lr + 32 * i) * ldb + (kk) + lk); }
; #define GEMM_STORES(buf) { u16* As_ = S + (buf) * TILE; u16* Bs_ = As_ + 128 * LS; \
;     _Pragma("unroll") for (int i = 0; i < 4; ++i) *(u32x4*)(As_ + (lr + 32 * i) * LS + lk) = ra[i]; \
;     _Pragma("unroll") for (int i = 0; i < 2 * NT; ++i) *(u32x4*)(Bs_ + (lr + 32 * i) * LS + lk) = rb[i]; }
; template <int NT>
; DI void gemm_main_np(f32x16 (&acc)[2][NT], const u16* __restrict__ A, int lda, int amode, const u16* __restrict__ Bt,
;                   int ldb, int K, char* smem) {
;     ...
;   GEMM_LOADG(0)
;   __syncthreads();
;   GEMM_STORES(0)
;   if (K > 64) GEMM_LOADG(64)
;   __syncthreads();
;   for (int k0 = 0; k0 < K; k0 += 64) {
;     const int cur = (k0 >> 6) & 1;
;     if (k0 + 64 < K) {
;       GEMM_STORES(cur ^ 1)
;       if (k0 + 128 < K) GEMM_LOADG(k0 + 128)
;     }
;     const u16* As = S + cur * TILE;
;     const u16* Bs = As + 128 * LS;
; #pragma unroll
;     for (int s = 0; s < 4; ++s) {
;       bf16x8 a[2], b[NT];
; #pragma unroll
;       for (int i = 0; i < 2; ++i) a[i] = *(const bf16x8*)(As + (wm * 64 + i * 32 + l31) * LS + s * 16 + hh * 8);
; #pragma unroll
;       for (int j = 0; j < NT; ++j) b[j] = *(const bf16x8*)(Bs + (wn * 32 * NT + j * 32 + l31) * LS + s * 16 + hh * 8);
; #pragma unroll
;       for (int i = 0; i < 2; ++i)
; #pragma unroll
;         for (int j = 0; j < NT; ++j) acc[i][j] = MFMA32(a[i], b[j], acc[i][j]);
;     }
;     __syncthreads();
	s_waitcnt vmcnt(5)
	ds_write_b128 v48, v[142:145]
	s_waitcnt vmcnt(4)
	ds_write_b128 v48, v[146:149] offset:4608
	s_waitcnt vmcnt(3)
	ds_write_b128 v48, v[150:153] offset:9216
	s_waitcnt vmcnt(2)
	ds_write_b128 v48, v[154:157] offset:13824
	s_waitcnt vmcnt(1)
	ds_write_b128 v48, v[158:161] offset:18432
	s_waitcnt vmcnt(0)
	ds_write_b128 v48, v[162:165] offset:23040
	global_load_dwordx4 v[142:145], v[36:37], off offset:896
	global_load_dwordx4 v[146:149], v[38:39], off offset:896
	global_load_dwordx4 v[150:153], v[40:41], off offset:896
	global_load_dwordx4 v[154:157], v[42:43], off offset:896
	global_load_dwordx4 v[158:161], v[44:45], off offset:896
	global_load_dwordx4 v[162:165], v[46:47], off offset:896
	v_mfma_f32_32x32x16_bf16 v[2:17], v[66:69], v[62:65], v[2:17]
	ds_read_b128 v[50:53], v34 offset:27648
	ds_read_b128 v[54:57], v35 offset:46080
	ds_read_b128 v[58:61], v34 offset:27680
	ds_read_b128 v[62:65], v35 offset:46112
	s_waitcnt lgkmcnt(2)
	v_mfma_f32_32x32x16_bf16 v[18:33], v[50:53], v[54:57], v[18:33]
	ds_read_b128 v[50:53], v34 offset:32256
	ds_read_b128 v[66:69], v34 offset:32288
	s_waitcnt lgkmcnt(1)
	v_mfma_f32_32x32x16_bf16 v[2:17], v[50:53], v[54:57], v[2:17]
	v_mfma_f32_32x32x16_bf16 v[18:33], v[58:61], v[62:65], v[18:33]
	s_waitcnt lgkmcnt(0)
	v_mfma_f32_32x32x16_bf16 v[2:17], v[66:69], v[62:65], v[2:17]
	ds_read_b128 v[50:53], v34 offset:27712
	ds_read_b128 v[54:57], v35 offset:46144
	ds_read_b128 v[58:61], v34 offset:27744
	ds_read_b128 v[62:65], v35 offset:46176
	s_waitcnt lgkmcnt(2)
	v_mfma_f32_32x32x16_bf16 v[18:33], v[50:53], v[54:57], v[18:33]
	ds_read_b128 v[50:53], v34 offset:32320
	ds_read_b128 v[66:69], v34 offset:32352
	s_waitcnt lgkmcnt(1)
	v_mfma_f32_32x32x16_bf16 v[2:17], v[50:53], v[54:57], v[2:17]
	v_mfma_f32_32x32x16_bf16 v[18:33], v[58:61], v[62:65], v[18:33]
	s_waitcnt lgkmcnt(0)
	s_barrier
	s_waitcnt vmcnt(5)
	ds_write_b128 v48, v[142:145] offset:27648
	s_waitcnt vmcnt(4)
	ds_write_b128 v48, v[146:149] offset:32256
	s_waitcnt vmcnt(3)
	ds_write_b128 v48, v[150:153] offset:36864
	s_waitcnt vmcnt(2)
	ds_write_b128 v48, v[154:157] offset:41472
	s_waitcnt vmcnt(1)
	ds_write_b128 v48, v[158:161] offset:46080
	s_waitcnt vmcnt(0)
	ds_write_b128 v48, v[162:165] offset:50688
	global_load_dwordx4 v[142:145], v[36:37], off offset:1024
	global_load_dwordx4 v[146:149], v[38:39], off offset:1024
	global_load_dwordx4 v[150:153], v[40:41], off offset:1024
	global_load_dwordx4 v[154:157], v[42:43], off offset:1024
	global_load_dwordx4 v[158:161], v[44:45], off offset:1024
	global_load_dwordx4 v[162:165], v[46:47], off offset:1024
	v_mfma_f32_32x32x16_bf16 v[2:17], v[66:69], v[62:65], v[2:17]
	ds_read_b128 v[50:53], v34
	ds_read_b128 v[54:57], v35 offset:18432
	ds_read_b128 v[58:61], v34 offset:32
	ds_read_b128 v[62:65], v35 offset:18464
	s_waitcnt lgkmcnt(2)
	v_mfma_f32_32x32x16_bf16 v[18:33], v[50:53], v[54:57], v[18:33]
	ds_read_b128 v[50:53], v34 offset:4608
	ds_read_b128 v[66:69], v34 offset:4640
	s_waitcnt lgkmcnt(1)
	v_mfma_f32_32x32x16_bf16 v[2:17], v[50:53], v[54:57], v[2:17]
	v_mfma_f32_32x32x16_bf16 v[18:33], v[58:61], v[62:65], v[18:33]
	s_waitcnt lgkmcnt(0)
	v_mfma_f32_32x32x16_bf16 v[2:17], v[66:69], v[62:65], v[2:17]
	ds_read_b128 v[50:53], v34 offset:64
	ds_read_b128 v[54:57], v35 offset:18496
	ds_read_b128 v[58:61], v34 offset:96
	ds_read_b128 v[62:65], v35 offset:18528
	s_waitcnt lgkmcnt(2)
	v_mfma_f32_32x32x16_bf16 v[18:33], v[50:53], v[54:57], v[18:33]
	ds_read_b128 v[50:53], v34 offset:4672
	ds_read_b128 v[66:69], v34 offset:4704
	s_waitcnt lgkmcnt(1)
	v_mfma_f32_32x32x16_bf16 v[2:17], v[50:53], v[54:57], v[2:17]
	v_mfma_f32_32x32x16_bf16 v[18:33], v[58:61], v[62:65], v[18:33]
	s_waitcnt lgkmcnt(0)
	s_barrier
	s_waitcnt vmcnt(5)
	ds_write_b128 v48, v[142:145]
	s_waitcnt vmcnt(4)
	ds_write_b128 v48, v[146:149] offset:4608
	s_waitcnt vmcnt(3)
	ds_write_b128 v48, v[150:153] offset:9216
	s_waitcnt vmcnt(2)
	ds_write_b128 v48, v[154:157] offset:13824
	s_waitcnt vmcnt(1)
	ds_write_b128 v48, v[158:161] offset:18432
	s_waitcnt vmcnt(0)
	ds_write_b128 v48, v[162:165] offset:23040
	global_load_dwordx4 v[142:145], v[36:37], off offset:1152
	global_load_dwordx4 v[146:149], v[38:39], off offset:1152
	global_load_dwordx4 v[150:153], v[40:41], off offset:1152
	global_load_dwordx4 v[154:157], v[42:43], off offset:1152
	global_load_dwordx4 v[158:161], v[44:45], off offset:1152
	global_load_dwordx4 v[162:165], v[46:47], off offset:1152
	v_mfma_f32_32x32x16_bf16 v[2:17], v[66:69], v[62:65], v[2:17]
	ds_read_b128 v[50:53], v34 offset:27648
	ds_read_b128 v[54:57], v35 offset:46080
	ds_read_b128 v[58:61], v34 offset:27680
	ds_read_b128 v[62:65], v35 offset:46112
	s_waitcnt lgkmcnt(2)
	v_mfma_f32_32x32x16_bf16 v[18:33], v[50:53], v[54:57], v[18:33]
	ds_read_b128 v[50:53], v34 offset:32256
	ds_read_b128 v[66:69], v34 offset:32288
	s_waitcnt lgkmcnt(1)
	v_mfma_f32_32x32x16_bf16 v[2:17], v[50:53], v[54:57], v[2:17]
	v_mfma_f32_32x32x16_bf16 v[18:33], v[58:61], v[62:65], v[18:33]
	s_waitcnt lgkmcnt(0)
	v_mfma_f32_32x32x16_bf16 v[2:17], v[66:69], v[62:65], v[2:17]
	ds_read_b128 v[50:53], v34 offset:27712
	ds_read_b128 v[54:57], v35 offset:46144
	ds_read_b128 v[58:61], v34 offset:27744
	ds_read_b128 v[62:65], v35 offset:46176
	s_waitcnt lgkmcnt(2)
	v_mfma_f32_32x32x16_bf16 v[18:33], v[50:53], v[54:57], v[18:33]
	ds_read_b128 v[50:53], v34 offset:32320
	ds_read_b128 v[66:69], v34 offset:32352
	s_waitcnt lgkmcnt(1)
	v_mfma_f32_32x32x16_bf16 v[2:17], v[50:53], v[54:57], v[2:17]
	v_mfma_f32_32x32x16_bf16 v[18:33], v[58:61], v[62:65], v[18:33]
	s_waitcnt lgkmcnt(0)
	s_barrier
; #define MFMA32(a, b, c) __builtin_amdgcn_mfma_f32_32x32x16_bf16((a), (b), (c), 0, 0, 0)
; #define GEMM_LOADG(kk) { const int ka_ = amode ? (((kk) >> 6) * 96) : (kk); \
;     _Pragma("unroll") for (int i = 0; i < 4; ++i) ra[i] = *(const u32x4*)(A + (size_t)(lr + 32 * i) * lda + ka_ + lk); \
;     _Pragma("unroll") for (int i = 0; i < 2 * NT; ++i) rb[i] = *(const u32x4*)(Bt + (size_t)(lr + 32 * i) * ldb + (kk) + lk); }
; #define GEMM_STORES(buf) { u16* As_ = S + (buf) * TILE; u16* Bs_ = As_ + 128 * LS; \
;     _Pragma("unroll") for (int i = 0; i < 4; ++i) *(u32x4*)(As_ + (lr + 32 * i) * LS + lk) = ra[i]; \
;     _Pragma("unroll") for (int i = 0; i < 2 * NT; ++i) *(u32x4*)(Bs_ + (lr + 32 * i) * LS + lk) = rb[i]; }
; template <int NT>
; DI void gemm_main_np(f32x16 (&acc)[2][NT], const u16* __restrict__ A, int lda, int amode, const u16* __restrict__ Bt,
;                   int ldb, int K, char* smem) {
;     ...
;   for (int k0 = 0; k0 < K; k0 += 64) {
;     const int cur = (k0 >> 6) & 1;
;     if (k0 + 64 < K) {
;       GEMM_STORES(cur ^ 1)
;       if (k0 + 128 < K) GEMM_LOADG(k0 + 128)
;     }
;     const u16* As = S + cur * TILE;
;     const u16* Bs = As + 128 * LS;
; #pragma unroll
;     for (int s = 0; s < 4; ++s) {
;       bf16x8 a[2], b[NT];
; #pragma unroll
;       for (int i = 0; i < 2; ++i) a[i] = *(const bf16x8*)(As + (wm * 64 + i * 32 + l31) * LS + s * 16 + hh * 8);
; #pragma unroll
;       for (int j = 0; j < NT; ++j) b[j] = *(const bf16x8*)(Bs + (wn * 32 * NT + j * 32 + l31) * LS + s * 16 + hh * 8);
; #pragma unroll
;       for (int i = 0; i < 2; ++i)
; #pragma unroll
;         for (int j = 0; j < NT; ++j) acc[i][j] = MFMA32(a[i], b[j], acc[i][j]);
;     }
;     __syncthreads();
;   }
	s_waitcnt vmcnt(5)
	ds_write_b128 v48, v[142:145] offset:27648
	s_waitcnt vmcnt(4)
	ds_write_b128 v48, v[146:149] offset:32256
	s_waitcnt vmcnt(3)
	ds_write_b128 v48, v[150:153] offset:36864
	s_waitcnt vmcnt(2)
	ds_write_b128 v48, v[154:157] offset:41472
	s_waitcnt vmcnt(1)
	ds_write_b128 v48, v[158:161] offset:46080
	s_waitcnt vmcnt(0)
	ds_write_b128 v48, v[162:165] offset:50688
	global_load_dwordx4 v[142:145], v[36:37], off offset:1280
	global_load_dwordx4 v[146:149], v[38:39], off offset:1280
	global_load_dwordx4 v[150:153], v[40:41], off offset:1280
	global_load_dwordx4 v[154:157], v[42:43], off offset:1280
	global_load_dwordx4 v[158:161], v[44:45], off offset:1280
	global_load_dwordx4 v[162:165], v[46:47], off offset:1280
	v_mfma_f32_32x32x16_bf16 v[2:17], v[66:69], v[62:65], v[2:17]
	ds_read_b128 v[50:53], v34
	ds_read_b128 v[54:57], v35 offset:18432
	ds_read_b128 v[58:61], v34 offset:32
	ds_read_b128 v[62:65], v35 offset:18464
	s_waitcnt lgkmcnt(2)
	v_mfma_f32_32x32x16_bf16 v[18:33], v[50:53], v[54:57], v[18:33]
	ds_read_b128 v[50:53], v34 offset:4608
	ds_read_b128 v[66:69], v34 offset:4640
	s_waitcnt lgkmcnt(1)
	v_mfma_f32_32x32x16_bf16 v[2:17], v[50:53], v[54:57], v[2:17]
	v_mfma_f32_32x32x16_bf16 v[18:33], v[58:61], v[62:65], v[18:33]
	s_waitcnt lgkmcnt(0)
	v_mfma_f32_32x32x16_bf16 v[2:17], v[66:69], v[62:65], v[2:17]
	ds_read_b128 v[50:53], v34 offset:64
	ds_read_b128 v[54:57], v35 offset:18496
	ds_read_b128 v[58:61], v34 offset:96
	ds_read_b128 v[62:65], v35 offset:18528
	s_waitcnt lgkmcnt(2)
	v_mfma_f32_32x32x16_bf16 v[18:33], v[50:53], v[54:57], v[18:33]
	ds_read_b128 v[50:53], v34 offset:4672
	ds_read_b128 v[66:69], v34 offset:4704
	s_waitcnt lgkmcnt(1)
	v_mfma_f32_32x32x16_bf16 v[2:17], v[50:53], v[54:57], v[2:17]
	v_mfma_f32_32x32x16_bf16 v[18:33], v[58:61], v[62:65], v[18:33]
	s_waitcnt lgkmcnt(0)
	s_barrier
	s_waitcnt vmcnt(5)
	ds_write_b128 v48, v[142:145]
	s_waitcnt vmcnt(4)
	ds_write_b128 v48, v[146:149] offset:4608
	s_waitcnt vmcnt(3)
	ds_write_b128 v48, v[150:153] offset:9216
	s_waitcnt vmcnt(2)
	ds_write_b128 v48, v[154:157] offset:13824
	s_waitcnt vmcnt(1)
	ds_write_b128 v48, v[158:161] offset:18432
	s_waitcnt vmcnt(0)
	ds_write_b128 v48, v[162:165] offset:23040
	global_load_dwordx4 v[142:145], v[36:37], off offset:1408
	global_load_dwordx4 v[146:149], v[38:39], off offset:1408
	global_load_dwordx4 v[150:153], v[40:41], off offset:1408
	global_load_dwordx4 v[154:157], v[42:43], off offset:1408
	global_load_dwordx4 v[158:161], v[44:45], off offset:1408
	global_load_dwordx4 v[162:165], v[46:47], off offset:1408
	v_mfma_f32_32x32x16_bf16 v[2:17], v[66:69], v[62:65], v[2:17]
	ds_read_b128 v[50:53], v34 offset:27648
	ds_read_b128 v[54:57], v35 offset:46080
	ds_read_b128 v[58:61], v34 offset:27680
	ds_read_b128 v[62:65], v35 offset:46112
	s_waitcnt lgkmcnt(2)
	v_mfma_f32_32x32x16_bf16 v[18:33], v[50:53], v[54:57], v[18:33]
	ds_read_b128 v[50:53], v34 offset:32256
	ds_read_b128 v[66:69], v34 offset:32288
	s_waitcnt lgkmcnt(1)
	v_mfma_f32_32x32x16_bf16 v[2:17], v[50:53], v[54:57], v[2:17]
	v_mfma_f32_32x32x16_bf16 v[18:33], v[58:61], v[62:65], v[18:33]
	s_waitcnt lgkmcnt(0)
	v_mfma_f32_32x32x16_bf16 v[2:17], v[66:69], v[62:65], v[2:17]
	ds_read_b128 v[50:53], v34 offset:27712
	ds_read_b128 v[54:57], v35 offset:46144
	ds_read_b128 v[58:61], v34 offset:27744
	ds_read_b128 v[62:65], v35 offset:46176
	s_waitcnt lgkmcnt(2)
	v_mfma_f32_32x32x16_bf16 v[18:33], v[50:53], v[54:57], v[18:33]
	ds_read_b128 v[50:53], v34 offset:32320
	ds_read_b128 v[66:69], v34 offset:32352
	s_waitcnt lgkmcnt(1)
	v_mfma_f32_32x32x16_bf16 v[2:17], v[50:53], v[54:57], v[2:17]
	v_mfma_f32_32x32x16_bf16 v[18:33], v[58:61], v[62:65], v[18:33]
	s_waitcnt lgkmcnt(0)
	s_barrier
	s_waitcnt vmcnt(5)
	ds_write_b128 v48, v[142:145] offset:27648
	s_waitcnt vmcnt(4)
	ds_write_b128 v48, v[146:149] offset:32256
	s_waitcnt vmcnt(3)
	ds_write_b128 v48, v[150:153] offset:36864
	s_waitcnt vmcnt(2)
	ds_write_b128 v48, v[154:157] offset:41472
	s_waitcnt vmcnt(1)
	ds_write_b128 v48, v[158:161] offset:46080
	s_waitcnt vmcnt(0)
	ds_write_b128 v48, v[162:165] offset:50688
	global_load_dwordx4 v[142:145], v[36:37], off offset:1536
	global_load_dwordx4 v[146:149], v[38:39], off offset:1536
	global_load_dwordx4 v[150:153], v[40:41], off offset:1536
	global_load_dwordx4 v[154:157], v[42:43], off offset:1536
	global_load_dwordx4 v[158:161], v[44:45], off offset:1536
	global_load_dwordx4 v[162:165], v[46:47], off offset:1536
	v_mfma_f32_32x32x16_bf16 v[2:17], v[66:69], v[62:65], v[2:17]
	ds_read_b128 v[50:53], v34
	ds_read_b128 v[54:57], v35 offset:18432
	ds_read_b128 v[58:61], v34 offset:32
	ds_read_b128 v[62:65], v35 offset:18464
	s_waitcnt lgkmcnt(2)
	v_mfma_f32_32x32x16_bf16 v[18:33], v[50:53], v[54:57], v[18:33]
	ds_read_b128 v[50:53], v34 offset:4608
	ds_read_b128 v[66:69], v34 offset:4640
	s_waitcnt lgkmcnt(1)
	v_mfma_f32_32x32x16_bf16 v[2:17], v[50:53], v[54:57], v[2:17]
	v_mfma_f32_32x32x16_bf16 v[18:33], v[58:61], v[62:65], v[18:33]
	s_waitcnt lgkmcnt(0)
	v_mfma_f32_32x32x16_bf16 v[2:17], v[66:69], v[62:65], v[2:17]
	ds_read_b128 v[50:53], v34 offset:64
	ds_read_b128 v[54:57], v35 offset:18496
	ds_read_b128 v[58:61], v34 offset:96
	ds_read_b128 v[62:65], v35 offset:18528
	s_waitcnt lgkmcnt(2)
	v_mfma_f32_32x32x16_bf16 v[18:33], v[50:53], v[54:57], v[18:33]
	ds_read_b128 v[50:53], v34 offset:4672
	ds_read_b128 v[66:69], v34 offset:4704
	s_waitcnt lgkmcnt(1)
	v_mfma_f32_32x32x16_bf16 v[2:17], v[50:53], v[54:57], v[2:17]
	v_mfma_f32_32x32x16_bf16 v[18:33], v[58:61], v[62:65], v[18:33]
	s_waitcnt lgkmcnt(0)
	s_barrier
; #define MFMA32(a, b, c) __builtin_amdgcn_mfma_f32_32x32x16_bf16((a), (b), (c), 0, 0, 0)
; #define GEMM_LOADG(kk) { const int ka_ = amode ? (((kk) >> 6) * 96) : (kk); \
;     _Pragma("unroll") for (int i = 0; i < 4; ++i) ra[i] = *(const u32x4*)(A + (size_t)(lr + 32 * i) * lda + ka_ + lk); \
;     _Pragma("unroll") for (int i = 0; i < 2 * NT; ++i) rb[i] = *(const u32x4*)(Bt + (size_t)(lr + 32 * i) * ldb + (kk) + lk); }
; #define GEMM_STORES(buf) { u16* As_ = S + (buf) * TILE; u16* Bs_ = As_ + 128 * LS; \
;     _Pragma("unroll") for (int i = 0; i < 4; ++i) *(u32x4*)(As_ + (lr + 32 * i) * LS + lk) = ra[i]; \
;     _Pragma("unroll") for (int i = 0; i < 2 * NT; ++i) *(u32x4*)(Bs_ + (lr + 32 * i) * LS + lk) = rb[i]; }
; template <int NT>
; DI void gemm_main_np(f32x16 (&acc)[2][NT], const u16* __restrict__ A, int lda, int amode, const u16* __restrict__ Bt,
;                   int ldb, int K, char* smem) {
;     ...
;   for (int k0 = 0; k0 < K; k0 += 64) {
;     const int cur = (k0 >> 6) & 1;
;     if (k0 + 64 < K) {
;       GEMM_STORES(cur ^ 1)
;       if (k0 + 128 < K) GEMM_LOADG(k0 + 128)
;     }
;     const u16* As = S + cur * TILE;
;     const u16* Bs = As + 128 * LS;
; #pragma unroll
;     for (int s = 0; s < 4; ++s) {
;       bf16x8 a[2], b[NT];
; #pragma unroll
;       for (int i = 0; i < 2; ++i) a[i] = *(const bf16x8*)(As + (wm * 64 + i * 32 + l31) * LS + s * 16 + hh * 8);
; #pragma unroll
;       for (int j = 0; j < NT; ++j) b[j] = *(const bf16x8*)(Bs + (wn * 32 * NT + j * 32 + l31) * LS + s * 16 + hh * 8);
; #pragma unroll
;       for (int i = 0; i < 2; ++i)
; #pragma unroll
;         for (int j = 0; j < NT; ++j) acc[i][j] = MFMA32(a[i], b[j], acc[i][j]);
;     }
;     __syncthreads();
;   }
	s_waitcnt vmcnt(5)
	ds_write_b128 v48, v[142:145]
	s_waitcnt vmcnt(4)
	ds_write_b128 v48, v[146:149] offset:4608
	s_waitcnt vmcnt(3)
	ds_write_b128 v48, v[150:153] offset:9216
	s_waitcnt vmcnt(2)
	ds_write_b128 v48, v[154:157] offset:13824
	s_waitcnt vmcnt(1)
	ds_write_b128 v48, v[158:161] offset:18432
	s_waitcnt vmcnt(0)
	ds_write_b128 v48, v[162:165] offset:23040
	global_load_dwordx4 v[142:145], v[36:37], off offset:1664
	global_load_dwordx4 v[146:149], v[38:39], off offset:1664
	global_load_dwordx4 v[150:153], v[40:41], off offset:1664
	global_load_dwordx4 v[154:157], v[42:43], off offset:1664
	global_load_dwordx4 v[158:161], v[44:45], off offset:1664
	global_load_dwordx4 v[162:165], v[46:47], off offset:1664
	v_mfma_f32_32x32x16_bf16 v[2:17], v[66:69], v[62:65], v[2:17]
	ds_read_b128 v[50:53], v34 offset:27648
	ds_read_b128 v[54:57], v35 offset:46080
	ds_read_b128 v[58:61], v34 offset:27680
	ds_read_b128 v[62:65], v35 offset:46112
	s_waitcnt lgkmcnt(2)
	v_mfma_f32_32x32x16_bf16 v[18:33], v[50:53], v[54:57], v[18:33]
	ds_read_b128 v[50:53], v34 offset:32256
	ds_read_b128 v[66:69], v34 offset:32288
	s_waitcnt lgkmcnt(1)
	v_mfma_f32_32x32x16_bf16 v[2:17], v[50:53], v[54:57], v[2:17]
	v_mfma_f32_32x32x16_bf16 v[18:33], v[58:61], v[62:65], v[18:33]
	s_waitcnt lgkmcnt(0)
	v_mfma_f32_32x32x16_bf16 v[2:17], v[66:69], v[62:65], v[2:17]
	ds_read_b128 v[50:53], v34 offset:27712
	ds_read_b128 v[54:57], v35 offset:46144
	ds_read_b128 v[58:61], v34 offset:27744
	ds_read_b128 v[62:65], v35 offset:46176
	s_waitcnt lgkmcnt(2)
	v_mfma_f32_32x32x16_bf16 v[18:33], v[50:53], v[54:57], v[18:33]
	ds_read_b128 v[50:53], v34 offset:32320
	ds_read_b128 v[66:69], v34 offset:32352
	s_waitcnt lgkmcnt(1)
	v_mfma_f32_32x32x16_bf16 v[2:17], v[50:53], v[54:57], v[2:17]
	v_mfma_f32_32x32x16_bf16 v[18:33], v[58:61], v[62:65], v[18:33]
	s_waitcnt lgkmcnt(0)
	s_barrier
	s_waitcnt vmcnt(5)
	ds_write_b128 v48, v[142:145] offset:27648
	s_waitcnt vmcnt(4)
	ds_write_b128 v48, v[146:149] offset:32256
	s_waitcnt vmcnt(3)
	ds_write_b128 v48, v[150:153] offset:36864
	s_waitcnt vmcnt(2)
	ds_write_b128 v48, v[154:157] offset:41472
	s_waitcnt vmcnt(1)
	ds_write_b128 v48, v[158:161] offset:46080
	s_waitcnt vmcnt(0)
	ds_write_b128 v48, v[162:165] offset:50688
	global_load_dwordx4 v[142:145], v[36:37], off offset:1792
	global_load_dwordx4 v[146:149], v[38:39], off offset:1792
	global_load_dwordx4 v[150:153], v[40:41], off offset:1792
	global_load_dwordx4 v[154:157], v[42:43], off offset:1792
	global_load_dwordx4 v[158:161], v[44:45], off offset:1792
	global_load_dwordx4 v[162:165], v[46:47], off offset:1792
	v_mfma_f32_32x32x16_bf16 v[2:17], v[66:69], v[62:65], v[2:17]
	ds_read_b128 v[50:53], v34
	ds_read_b128 v[54:57], v35 offset:18432
	ds_read_b128 v[58:61], v34 offset:32
	ds_read_b128 v[62:65], v35 offset:18464
	s_waitcnt lgkmcnt(2)
	v_mfma_f32_32x32x16_bf16 v[18:33], v[50:53], v[54:57], v[18:33]
	ds_read_b128 v[50:53], v34 offset:4608
	ds_read_b128 v[66:69], v34 offset:4640
	s_waitcnt lgkmcnt(1)
	v_mfma_f32_32x32x16_bf16 v[2:17], v[50:53], v[54:57], v[2:17]
	v_mfma_f32_32x32x16_bf16 v[18:33], v[58:61], v[62:65], v[18:33]
	s_waitcnt lgkmcnt(0)
	v_mfma_f32_32x32x16_bf16 v[2:17], v[66:69], v[62:65], v[2:17]
	ds_read_b128 v[50:53], v34 offset:64
	ds_read_b128 v[54:57], v35 offset:18496
	ds_read_b128 v[58:61], v34 offset:96
	ds_read_b128 v[62:65], v35 offset:18528
	s_waitcnt lgkmcnt(2)
	v_mfma_f32_32x32x16_bf16 v[18:33], v[50:53], v[54:57], v[18:33]
	ds_read_b128 v[50:53], v34 offset:4672
	ds_read_b128 v[66:69], v34 offset:4704
	s_waitcnt lgkmcnt(1)
	v_mfma_f32_32x32x16_bf16 v[2:17], v[50:53], v[54:57], v[2:17]
	v_mfma_f32_32x32x16_bf16 v[18:33], v[58:61], v[62:65], v[18:33]
	s_waitcnt lgkmcnt(0)
	s_barrier
; #define MFMA32(a, b, c) __builtin_amdgcn_mfma_f32_32x32x16_bf16((a), (b), (c), 0, 0, 0)
; #define GEMM_LOADG(kk) { const int ka_ = amode ? (((kk) >> 6) * 96) : (kk); \
;     _Pragma("unroll") for (int i = 0; i < 4; ++i) ra[i] = *(const u32x4*)(A + (size_t)(lr + 32 * i) * lda + ka_ + lk); \
;     _Pragma("unroll") for (int i = 0; i < 2 * NT; ++i) rb[i] = *(const u32x4*)(Bt + (size_t)(lr + 32 * i) * ldb + (kk) + lk); }
; #define GEMM_STORES(buf) { u16* As_ = S + (buf) * TILE; u16* Bs_ = As_ + 128 * LS; \
;     _Pragma("unroll") for (int i = 0; i < 4; ++i) *(u32x4*)(As_ + (lr + 32 * i) * LS + lk) = ra[i]; \
;     _Pragma("unroll") for (int i = 0; i < 2 * NT; ++i) *(u32x4*)(Bs_ + (lr + 32 * i) * LS + lk) = rb[i]; }
; template <int NT>
; DI void gemm_main_np(f32x16 (&acc)[2][NT], const u16* __restrict__ A, int lda, int amode, const u16* __restrict__ Bt,
;                   int ldb, int K, char* smem) {
;     ...
;   for (int k0 = 0; k0 < K; k0 += 64) {
;     const int cur = (k0 >> 6) & 1;
;     if (k0 + 64 < K) {
;       GEMM_STORES(cur ^ 1)
;       if (k0 + 128 < K) GEMM_LOADG(k0 + 128)
;     }
;     const u16* As = S + cur * TILE;
;     const u16* Bs = As + 128 * LS;
; #pragma unroll
;     for (int s = 0; s < 4; ++s) {
;       bf16x8 a[2], b[NT];
; #pragma unroll
;       for (int i = 0; i < 2; ++i) a[i] = *(const bf16x8*)(As + (wm * 64 + i * 32 + l31) * LS + s * 16 + hh * 8);
; #pragma unroll
;       for (int j = 0; j < NT; ++j) b[j] = *(const bf16x8*)(Bs + (wn * 32 * NT + j * 32 + l31) * LS + s * 16 + hh * 8);
; #pragma unroll
;       for (int i = 0; i < 2; ++i)
; #pragma unroll
;         for (int j = 0; j < NT; ++j) acc[i][j] = MFMA32(a[i], b[j], acc[i][j]);
;     }
;     __syncthreads();
;   }
; DI void p5_merge_half(KP p, int u, int mt_off, char* smem) {
;     ...
;     const u16* A;
;     int lda, amode = 0;
;     if (br == 0) { A = (const u16*)(p->ws + OFF_Q) + (size_t)mt * 128 * 768; lda = 768; amode = 1; }
	s_waitcnt vmcnt(5)
	ds_write_b128 v48, v[142:145]
	s_waitcnt vmcnt(4)
	ds_write_b128 v48, v[146:149] offset:4608
	s_waitcnt vmcnt(3)
	ds_write_b128 v48, v[150:153] offset:9216
	s_waitcnt vmcnt(2)
	ds_write_b128 v48, v[154:157] offset:13824
	s_waitcnt vmcnt(1)
	ds_write_b128 v48, v[158:161] offset:18432
	s_waitcnt vmcnt(0)
	ds_write_b128 v48, v[162:165] offset:23040
	global_load_dwordx4 v[142:145], v[36:37], off offset:1920
	global_load_dwordx4 v[146:149], v[38:39], off offset:1920
	global_load_dwordx4 v[150:153], v[40:41], off offset:1920
	global_load_dwordx4 v[154:157], v[42:43], off offset:1920
	global_load_dwordx4 v[158:161], v[44:45], off offset:1920
	global_load_dwordx4 v[162:165], v[46:47], off offset:1920
	v_mfma_f32_32x32x16_bf16 v[2:17], v[66:69], v[62:65], v[2:17]
	ds_read_b128 v[50:53], v34 offset:27648
	ds_read_b128 v[54:57], v35 offset:46080
	ds_read_b128 v[58:61], v34 offset:27680
	ds_read_b128 v[62:65], v35 offset:46112
	s_waitcnt lgkmcnt(2)
	v_mfma_f32_32x32x16_bf16 v[18:33], v[50:53], v[54:57], v[18:33]
	ds_read_b128 v[50:53], v34 offset:32256
	ds_read_b128 v[66:69], v34 offset:32288
	s_waitcnt lgkmcnt(1)
	v_mfma_f32_32x32x16_bf16 v[2:17], v[50:53], v[54:57], v[2:17]
	v_mfma_f32_32x32x16_bf16 v[18:33], v[58:61], v[62:65], v[18:33]
	s_waitcnt lgkmcnt(0)
	v_mfma_f32_32x32x16_bf16 v[2:17], v[66:69], v[62:65], v[2:17]
	ds_read_b128 v[50:53], v34 offset:27712
	ds_read_b128 v[54:57], v35 offset:46144
	ds_read_b128 v[58:61], v34 offset:27744
	ds_read_b128 v[62:65], v35 offset:46176
	s_waitcnt lgkmcnt(2)
	v_mfma_f32_32x32x16_bf16 v[18:33], v[50:53], v[54:57], v[18:33]
	ds_read_b128 v[50:53], v34 offset:32320
	ds_read_b128 v[66:69], v34 offset:32352
	s_waitcnt lgkmcnt(1)
	v_mfma_f32_32x32x16_bf16 v[2:17], v[50:53], v[54:57], v[2:17]
	s_nop 0
	s_nop 0
	s_nop 0
	v_mfma_f32_32x32x16_bf16 v[18:33], v[58:61], v[62:65], v[18:33]
	s_nop 0
	s_waitcnt lgkmcnt(0)
	s_barrier
	s_waitcnt vmcnt(5)
	ds_write_b128 v48, v[142:145] offset:27648
	s_waitcnt vmcnt(4)
	ds_write_b128 v48, v[146:149] offset:32256
	s_waitcnt vmcnt(3)
	ds_write_b128 v48, v[150:153] offset:36864
	s_waitcnt vmcnt(2)
	ds_write_b128 v48, v[154:157] offset:41472
	s_waitcnt vmcnt(1)
	ds_write_b128 v48, v[158:161] offset:46080
	s_waitcnt vmcnt(0)
	ds_write_b128 v48, v[162:165] offset:50688
	v_mfma_f32_32x32x16_bf16 v[2:17], v[66:69], v[62:65], v[2:17]
	ds_read_b128 v[36:39], v34
	ds_read_b128 v[40:43], v35 offset:18432
	ds_read_b128 v[44:47], v34 offset:32
	ds_read_b128 v[48:51], v35 offset:18464
	s_waitcnt lgkmcnt(2)
	v_mfma_f32_32x32x16_bf16 v[18:33], v[36:39], v[40:43], v[18:33]
	ds_read_b128 v[36:39], v34 offset:4608
	ds_read_b128 v[52:55], v34 offset:4640
	s_waitcnt lgkmcnt(1)
	v_mfma_f32_32x32x16_bf16 v[2:17], v[36:39], v[40:43], v[2:17]
	v_mfma_f32_32x32x16_bf16 v[18:33], v[44:47], v[48:51], v[18:33]
	s_waitcnt lgkmcnt(0)
	v_mfma_f32_32x32x16_bf16 v[2:17], v[52:55], v[48:51], v[2:17]
	ds_read_b128 v[36:39], v34 offset:64
	ds_read_b128 v[40:43], v35 offset:18496
	ds_read_b128 v[44:47], v34 offset:96
	ds_read_b128 v[48:51], v35 offset:18528
	s_waitcnt lgkmcnt(2)
	v_mfma_f32_32x32x16_bf16 v[18:33], v[36:39], v[40:43], v[18:33]
	ds_read_b128 v[36:39], v34 offset:4672
	ds_read_b128 v[52:55], v34 offset:4704
	s_waitcnt lgkmcnt(0)
	s_barrier
	v_mfma_f32_32x32x16_bf16 v[2:17], v[36:39], v[40:43], v[2:17]
	v_mfma_f32_32x32x16_bf16 v[18:33], v[44:47], v[48:51], v[18:33]
	v_mfma_f32_32x32x16_bf16 v[2:17], v[52:55], v[48:51], v[2:17]
	ds_read_b128 v[36:39], v34 offset:27648
	ds_read_b128 v[40:43], v35 offset:46080
	ds_read_b128 v[44:47], v35 offset:46112
	ds_read_b128 v[48:51], v34 offset:27680
	s_waitcnt lgkmcnt(2)
	v_mfma_f32_32x32x16_bf16 v[18:33], v[36:39], v[40:43], v[18:33]
	ds_read_b128 v[36:39], v34 offset:32256
	ds_read_b128 v[52:55], v34 offset:32288
	s_waitcnt lgkmcnt(1)
	v_mfma_f32_32x32x16_bf16 v[2:17], v[36:39], v[40:43], v[2:17]
	v_mfma_f32_32x32x16_bf16 v[18:33], v[48:51], v[44:47], v[18:33]
	s_waitcnt lgkmcnt(0)
	v_mfma_f32_32x32x16_bf16 v[2:17], v[52:55], v[44:47], v[2:17]
	ds_read_b128 v[36:39], v34 offset:27712
	ds_read_b128 v[40:43], v35 offset:46144
	ds_read_b128 v[44:47], v34 offset:27744
	ds_read_b128 v[48:51], v35 offset:46176
	s_waitcnt lgkmcnt(2)
	v_mfma_f32_32x32x16_bf16 v[18:33], v[36:39], v[40:43], v[18:33]
	ds_read_b128 v[36:39], v34 offset:32320
	ds_read_b128 v[52:55], v34 offset:32352
	s_waitcnt lgkmcnt(0)
	s_barrier
	v_mfma_f32_32x32x16_bf16 v[2:17], v[36:39], v[40:43], v[2:17]
	v_mfma_f32_32x32x16_bf16 v[18:33], v[44:47], v[48:51], v[18:33]
	v_mfma_f32_32x32x16_bf16 v[2:17], v[52:55], v[48:51], v[2:17]
	s_cbranch_scc1 .LBB0_1721
	s_cmp_lg_u32 s29, 1
	s_mov_b64 s[18:19], -1
	s_cbranch_scc0 .LBB0_1719
	s_mov_b64 s[18:19], 0

; #define MFMA32(a, b, c) __builtin_amdgcn_mfma_f32_32x32x16_bf16((a), (b), (c), 0, 0, 0)
; DI int tidx() { int t = __builtin_amdgcn_workitem_id_x(); asm volatile("" : "+v"(t)); return t; }
; #define GEMM_LOADG(kk) { const int ka_ = amode ? (((kk) >> 6) * 96) : (kk); \
;     _Pragma("unroll") for (int i = 0; i < 4; ++i) ra[i] = *(const u32x4*)(A + (size_t)(lr + 32 * i) * lda + ka_ + lk); \
;     _Pragma("unroll") for (int i = 0; i < 2 * NT; ++i) rb[i] = *(const u32x4*)(Bt + (size_t)(lr + 32 * i) * ldb + (kk) + lk); }
; template <int NT>
; DI void gemm_main_np(f32x16 (&acc)[2][NT], const u16* __restrict__ A, int lda, int amode, const u16* __restrict__ Bt,
;                   int ldb, int K, char* smem) {
;     ...
;   const int tid = tidx(), lane = tid & 63, w = tid >> 6, wm = w >> 1, wn = w & 1;
;   const int l31 = lane & 31, hh = lane >> 5;
;   const int lr = tid >> 3, lk = (tid & 7) * 8;
;   u32x4 ra[4], rb[2 * NT];
;     ...
;   GEMM_LOADG(0)
;   __syncthreads();
;   GEMM_STORES(0)
;   if (K > 64) GEMM_LOADG(64)
;   __syncthreads();
;   for (int k0 = 0; k0 < K; k0 += 64) {
;     const int cur = (k0 >> 6) & 1;
;     if (k0 + 64 < K) {
;       GEMM_STORES(cur ^ 1)
;       if (k0 + 128 < K) GEMM_LOADG(k0 + 128)
;     }
;     const u16* As = S + cur * TILE;
;     const u16* Bs = As + 128 * LS;
; #pragma unroll
;     for (int s = 0; s < 4; ++s) {
;       bf16x8 a[2], b[NT];
; #pragma unroll
;       for (int i = 0; i < 2; ++i) a[i] = *(const bf16x8*)(As + (wm * 64 + i * 32 + l31) * LS + s * 16 + hh * 8);
; #pragma unroll
;       for (int j = 0; j < NT; ++j) b[j] = *(const bf16x8*)(Bs + (wn * 32 * NT + j * 32 + l31) * LS + s * 16 + hh * 8);
; #pragma unroll
;       for (int i = 0; i < 2; ++i)
; #pragma unroll
;         for (int j = 0; j < NT; ++j) acc[i][j] = MFMA32(a[i], b[j], acc[i][j]);
;     }
;     __syncthreads();
;   }
; DI void resid_ctx_half(KP p, int l, int u, int which, const u16* A, int K, const u16* Wt, const float* xin, float* xout, char* smem) {
;   const int mt = 128 + (u >> 4), nt = u & 15;
;   const int lane = tidx() & 63, w = tidx() >> 6, wm = w >> 1, wn = w & 1, l31 = lane & 31, hh = lane >> 5;
;   f32x16 acc[2][1];
;   zero_acc(acc[0][0]); zero_acc(acc[1][0]);
;   gemm_main_np<1>(acc, A + (size_t)mt * 128 * K, K, 0, Wt + (size_t)nt * 64 * K, K, K, smem);
.LBB0_1791:
	s_mov_b64 s[2:3], s[0:1]
	s_add_i32 s18, s28, 0xfffffe00
	s_load_dwordx2 s[16:17], s[2:3], 0x130
	s_lshl_b32 s2, s18, 3
	s_and_b32 s2, s2, 0x380
	v_mov_b32_e32 v50, v0
	v_mov_b32_e32 v51, v0
	s_lshl_b32 s3, s2, 11
	v_mov_b32_e32 v54, v0
	s_add_u32 s4, s38, s3
	s_addc_u32 s5, s39, 0
	v_lshlrev_b32_e32 v2, 4, v54
	v_ashrrev_i32_e32 v26, 3, v54
	v_and_b32_e32 v198, 0x70, v2
	s_lshl_b32 s3, s18, 6
	v_lshl_add_u64 v[28:29], s[4:5], 0, v[198:199]
	s_mov_b64 s[4:5], 0xc6d0000
	v_ashrrev_i32_e32 v27, 31, v26
	s_and_b32 s3, s3, 0x3c0
	v_lshl_add_u64 v[14:15], v[28:29], 0, s[4:5]
	v_lshlrev_b64 v[30:31], 11, v[26:27]
	s_mov_b64 s[4:5], 0x10000
	s_lshl_b32 s18, s3, 11
	v_lshl_add_u64 v[38:39], v[14:15], 0, v[30:31]
	v_lshl_add_u64 v[32:33], v[30:31], 0, s[4:5]
	s_mov_b64 s[4:5], 0x20000
	s_add_u32 s18, s43, s18
	global_load_dwordx4 v[2:5], v[38:39], off
	v_lshl_add_u64 v[40:41], v[14:15], 0, v[32:33]
	v_lshl_add_u64 v[36:37], v[30:31], 0, s[4:5]
	s_mov_b64 s[4:5], 0x30000
	s_addc_u32 s19, s42, 0
	global_load_dwordx4 v[6:9], v[40:41], off
	v_lshl_add_u64 v[42:43], v[14:15], 0, v[36:37]
	v_lshl_add_u64 v[52:53], v[30:31], 0, s[4:5]
	global_load_dwordx4 v[10:13], v[42:43], off
	v_lshl_add_u64 v[44:45], v[14:15], 0, v[52:53]
	v_lshl_add_u64 v[22:23], s[18:19], 0, v[198:199]
	global_load_dwordx4 v[14:17], v[44:45], off
	v_lshl_add_u64 v[46:47], v[22:23], 0, v[30:31]
	global_load_dwordx4 v[18:21], v[46:47], off
	v_lshl_add_u64 v[48:49], v[22:23], 0, v[32:33]
	global_load_dwordx4 v[22:25], v[48:49], off
	v_mad_u64_u32 v[34:35], s[4:5], v26, s60, v[198:199]
	s_mov_b64 s[4:5], 0xc6d0080
	s_waitcnt lgkmcnt(0)
	s_barrier
	v_and_b32_e32 v27, 31, v54
	s_add_u32 s16, s16, 0xe420000
	s_addc_u32 s17, s17, 0
	s_waitcnt vmcnt(5)
	ds_write_b128 v34, v[2:5]
	s_waitcnt vmcnt(4)
	ds_write_b128 v34, v[6:9] offset:4608
	s_waitcnt vmcnt(3)
	ds_write_b128 v34, v[10:13] offset:9216
	s_waitcnt vmcnt(2)
	ds_write_b128 v34, v[14:17] offset:13824
	s_waitcnt vmcnt(1)
	ds_write_b128 v34, v[18:21] offset:18432
	s_waitcnt vmcnt(0)
	ds_write_b128 v34, v[22:25] offset:23040
	v_lshl_add_u64 v[14:15], v[28:29], 0, s[4:5]
	v_lshl_add_u64 v[2:3], v[14:15], 0, v[30:31]
	global_load_dwordx4 v[2:5], v[2:3], off
	v_lshl_add_u64 v[6:7], v[14:15], 0, v[32:33]
	global_load_dwordx4 v[6:9], v[6:7], off
	v_lshl_add_u64 v[10:11], v[14:15], 0, v[36:37]
	global_load_dwordx4 v[10:13], v[10:11], off
	v_lshl_add_u64 v[14:15], v[14:15], 0, v[52:53]
	v_lshl_add_u64 v[18:19], s[18:19], 0, v[30:31]
	global_load_dwordx4 v[14:17], v[14:15], off
	v_lshl_add_u64 v[18:19], v[18:19], 0, v[198:199]
	v_lshl_add_u64 v[22:23], s[18:19], 0, v[32:33]
	global_load_dwordx4 v[18:21], v[18:19], off offset:128
	v_lshl_add_u64 v[22:23], v[22:23], 0, v[198:199]
	global_load_dwordx4 v[22:25], v[22:23], off offset:128
	s_waitcnt lgkmcnt(0)
	s_barrier
	v_lshrrev_b32_e32 v28, 1, v54
	v_and_or_b32 v29, v28, s31, v27
	v_and_b32_e32 v26, 16, v28
	v_and_or_b32 v27, v28, 32, v27
	v_mad_u64_u32 v[36:37], s[4:5], v29, s60, v[26:27]
	v_mad_u32_u24 v35, v27, s60, v26
	s_waitcnt vmcnt(5)
	ds_write_b128 v34, v[2:5] offset:27648
	s_waitcnt vmcnt(4)
	ds_write_b128 v34, v[6:9] offset:32256
	s_waitcnt vmcnt(3)
	ds_write_b128 v34, v[10:13] offset:36864
	s_waitcnt vmcnt(2)
	ds_write_b128 v34, v[14:17] offset:41472
	s_waitcnt vmcnt(1)
	ds_write_b128 v34, v[18:21] offset:46080
	s_waitcnt vmcnt(0)
	ds_write_b128 v34, v[22:25] offset:50688
	global_load_dwordx4 v[52:55], v[38:39], off offset:256
	global_load_dwordx4 v[56:59], v[40:41], off offset:256
	global_load_dwordx4 v[60:63], v[42:43], off offset:256
	global_load_dwordx4 v[64:67], v[44:45], off offset:256
	global_load_dwordx4 v[68:71], v[46:47], off offset:256
	global_load_dwordx4 v[72:75], v[48:49], off offset:256
	ds_read_b128 v[2:5], v36 offset:4608
	ds_read_b128 v[6:9], v36
	ds_read_b128 v[76:79], v36 offset:32
	ds_read_b128 v[10:13], v35 offset:18432
	ds_read_b128 v[80:83], v35 offset:18464
	ds_read_b128 v[84:87], v36 offset:4640
	s_waitcnt lgkmcnt(2)
	v_mfma_f32_32x32x16_bf16 v[18:33], v[6:9], v[10:13], 0
	v_mfma_f32_32x32x16_bf16 v[2:17], v[2:5], v[10:13], 0
	s_waitcnt lgkmcnt(1)
	v_mfma_f32_32x32x16_bf16 v[18:33], v[76:79], v[80:83], v[18:33]
	s_waitcnt lgkmcnt(0)
	v_mfma_f32_32x32x16_bf16 v[2:17], v[84:87], v[80:83], v[2:17]
	ds_read_b128 v[76:79], v36 offset:64
	ds_read_b128 v[80:83], v36 offset:4672
	ds_read_b128 v[84:87], v35 offset:18496
	s_waitcnt lgkmcnt(0)
	v_mfma_f32_32x32x16_bf16 v[18:33], v[76:79], v[84:87], v[18:33]
	v_mfma_f32_32x32x16_bf16 v[2:17], v[80:83], v[84:87], v[2:17]
	ds_read_b128 v[76:79], v36 offset:96
	ds_read_b128 v[80:83], v36 offset:4704
	ds_read_b128 v[84:87], v35 offset:18528
	s_waitcnt lgkmcnt(0)
	s_barrier
	s_waitcnt vmcnt(5)
	ds_write_b128 v34, v[52:55]
	s_waitcnt vmcnt(4)
	ds_write_b128 v34, v[56:59] offset:4608
	s_waitcnt vmcnt(3)
	ds_write_b128 v34, v[60:63] offset:9216
	s_waitcnt vmcnt(2)
	ds_write_b128 v34, v[64:67] offset:13824
	s_waitcnt vmcnt(1)
	ds_write_b128 v34, v[68:71] offset:18432
	s_waitcnt vmcnt(0)
	ds_write_b128 v34, v[72:75] offset:23040
	global_load_dwordx4 v[52:55], v[38:39], off offset:384
	global_load_dwordx4 v[56:59], v[40:41], off offset:384
	global_load_dwordx4 v[60:63], v[42:43], off offset:384
	global_load_dwordx4 v[64:67], v[44:45], off offset:384
	global_load_dwordx4 v[68:71], v[46:47], off offset:384
	global_load_dwordx4 v[72:75], v[48:49], off offset:384
	v_mfma_f32_32x32x16_bf16 v[2:17], v[80:83], v[84:87], v[2:17]
	v_mfma_f32_32x32x16_bf16 v[18:33], v[76:79], v[84:87], v[18:33]
	ds_read_b128 v[76:79], v36 offset:32256
	ds_read_b128 v[80:83], v36 offset:27648
	ds_read_b128 v[84:87], v36 offset:27680
	ds_read_b128 v[88:91], v35 offset:46080
	ds_read_b128 v[92:95], v35 offset:46112
	s_waitcnt lgkmcnt(1)
	v_mfma_f32_32x32x16_bf16 v[2:17], v[76:79], v[88:91], v[2:17]
	ds_read_b128 v[76:79], v36 offset:32288
	v_mfma_f32_32x32x16_bf16 v[18:33], v[80:83], v[88:91], v[18:33]
	s_waitcnt lgkmcnt(1)
	v_mfma_f32_32x32x16_bf16 v[18:33], v[84:87], v[92:95], v[18:33]
	s_waitcnt lgkmcnt(0)
	v_mfma_f32_32x32x16_bf16 v[2:17], v[76:79], v[92:95], v[2:17]
	ds_read_b128 v[76:79], v36 offset:27712
	ds_read_b128 v[80:83], v36 offset:32320
	ds_read_b128 v[84:87], v35 offset:46144
	s_waitcnt lgkmcnt(0)
	v_mfma_f32_32x32x16_bf16 v[18:33], v[76:79], v[84:87], v[18:33]
	v_mfma_f32_32x32x16_bf16 v[2:17], v[80:83], v[84:87], v[2:17]
	ds_read_b128 v[76:79], v36 offset:27744
	ds_read_b128 v[80:83], v36 offset:32352
	ds_read_b128 v[84:87], v35 offset:46176
	s_waitcnt lgkmcnt(0)
	s_barrier
; #define MFMA32(a, b, c) __builtin_amdgcn_mfma_f32_32x32x16_bf16((a), (b), (c), 0, 0, 0)
; #define GEMM_LOADG(kk) { const int ka_ = amode ? (((kk) >> 6) * 96) : (kk); \
;     _Pragma("unroll") for (int i = 0; i < 4; ++i) ra[i] = *(const u32x4*)(A + (size_t)(lr + 32 * i) * lda + ka_ + lk); \
;     _Pragma("unroll") for (int i = 0; i < 2 * NT; ++i) rb[i] = *(const u32x4*)(Bt + (size_t)(lr + 32 * i) * ldb + (kk) + lk); }
; #define GEMM_STORES(buf) { u16* As_ = S + (buf) * TILE; u16* Bs_ = As_ + 128 * LS; \
;     _Pragma("unroll") for (int i = 0; i < 4; ++i) *(u32x4*)(As_ + (lr + 32 * i) * LS + lk) = ra[i]; \
;     _Pragma("unroll") for (int i = 0; i < 2 * NT; ++i) *(u32x4*)(Bs_ + (lr + 32 * i) * LS + lk) = rb[i]; }
; template <int NT>
; DI void gemm_main_np(f32x16 (&acc)[2][NT], const u16* __restrict__ A, int lda, int amode, const u16* __restrict__ Bt,
;                   int ldb, int K, char* smem) {
;     ...
;   for (int k0 = 0; k0 < K; k0 += 64) {
;     const int cur = (k0 >> 6) & 1;
;     if (k0 + 64 < K) {
;       GEMM_STORES(cur ^ 1)
;       if (k0 + 128 < K) GEMM_LOADG(k0 + 128)
;     }
;     const u16* As = S + cur * TILE;
;     const u16* Bs = As + 128 * LS;
; #pragma unroll
;     for (int s = 0; s < 4; ++s) {
;       bf16x8 a[2], b[NT];
; #pragma unroll
;       for (int i = 0; i < 2; ++i) a[i] = *(const bf16x8*)(As + (wm * 64 + i * 32 + l31) * LS + s * 16 + hh * 8);
; #pragma unroll
;       for (int j = 0; j < NT; ++j) b[j] = *(const bf16x8*)(Bs + (wn * 32 * NT + j * 32 + l31) * LS + s * 16 + hh * 8);
; #pragma unroll
;       for (int i = 0; i < 2; ++i)
; #pragma unroll
;         for (int j = 0; j < NT; ++j) acc[i][j] = MFMA32(a[i], b[j], acc[i][j]);
;     }
	s_waitcnt vmcnt(5)
	ds_write_b128 v34, v[52:55] offset:27648
	s_waitcnt vmcnt(4)
	ds_write_b128 v34, v[56:59] offset:32256
	s_waitcnt vmcnt(3)
	ds_write_b128 v34, v[60:63] offset:36864
	s_waitcnt vmcnt(2)
	ds_write_b128 v34, v[64:67] offset:41472
	s_waitcnt vmcnt(1)
	ds_write_b128 v34, v[68:71] offset:46080
	s_waitcnt vmcnt(0)
	ds_write_b128 v34, v[72:75] offset:50688
	global_load_dwordx4 v[52:55], v[38:39], off offset:512
	global_load_dwordx4 v[56:59], v[40:41], off offset:512
	global_load_dwordx4 v[60:63], v[42:43], off offset:512
	global_load_dwordx4 v[64:67], v[44:45], off offset:512
	global_load_dwordx4 v[68:71], v[46:47], off offset:512
	global_load_dwordx4 v[72:75], v[48:49], off offset:512
	v_mfma_f32_32x32x16_bf16 v[2:17], v[80:83], v[84:87], v[2:17]
	v_mfma_f32_32x32x16_bf16 v[18:33], v[76:79], v[84:87], v[18:33]
	ds_read_b128 v[76:79], v36 offset:4608
	ds_read_b128 v[80:83], v36
	ds_read_b128 v[84:87], v36 offset:32
	ds_read_b128 v[88:91], v35 offset:18432
	ds_read_b128 v[92:95], v35 offset:18464
	s_waitcnt lgkmcnt(1)
	v_mfma_f32_32x32x16_bf16 v[2:17], v[76:79], v[88:91], v[2:17]
	ds_read_b128 v[76:79], v36 offset:4640
	v_mfma_f32_32x32x16_bf16 v[18:33], v[80:83], v[88:91], v[18:33]
	s_waitcnt lgkmcnt(1)
	v_mfma_f32_32x32x16_bf16 v[18:33], v[84:87], v[92:95], v[18:33]
	s_waitcnt lgkmcnt(0)
	v_mfma_f32_32x32x16_bf16 v[2:17], v[76:79], v[92:95], v[2:17]
	ds_read_b128 v[76:79], v36 offset:64
	ds_read_b128 v[80:83], v36 offset:4672
	ds_read_b128 v[84:87], v35 offset:18496
	s_waitcnt lgkmcnt(0)
	v_mfma_f32_32x32x16_bf16 v[18:33], v[76:79], v[84:87], v[18:33]
	v_mfma_f32_32x32x16_bf16 v[2:17], v[80:83], v[84:87], v[2:17]
	ds_read_b128 v[76:79], v36 offset:96
	ds_read_b128 v[80:83], v36 offset:4704
	ds_read_b128 v[84:87], v35 offset:18528
	s_waitcnt lgkmcnt(0)
	s_barrier
	s_waitcnt vmcnt(5)
	ds_write_b128 v34, v[52:55]
	s_waitcnt vmcnt(4)
	ds_write_b128 v34, v[56:59] offset:4608
	s_waitcnt vmcnt(3)
	ds_write_b128 v34, v[60:63] offset:9216
	s_waitcnt vmcnt(2)
	ds_write_b128 v34, v[64:67] offset:13824
	s_waitcnt vmcnt(1)
	ds_write_b128 v34, v[68:71] offset:18432
	s_waitcnt vmcnt(0)
	ds_write_b128 v34, v[72:75] offset:23040
	global_load_dwordx4 v[52:55], v[38:39], off offset:640
	global_load_dwordx4 v[56:59], v[40:41], off offset:640
	global_load_dwordx4 v[60:63], v[42:43], off offset:640
	global_load_dwordx4 v[64:67], v[44:45], off offset:640
	global_load_dwordx4 v[68:71], v[46:47], off offset:640
	global_load_dwordx4 v[72:75], v[48:49], off offset:640
	v_mfma_f32_32x32x16_bf16 v[2:17], v[80:83], v[84:87], v[2:17]
	v_mfma_f32_32x32x16_bf16 v[18:33], v[76:79], v[84:87], v[18:33]
	ds_read_b128 v[76:79], v36 offset:32256
	ds_read_b128 v[80:83], v36 offset:27648
	ds_read_b128 v[84:87], v36 offset:27680
	ds_read_b128 v[88:91], v35 offset:46080
	ds_read_b128 v[92:95], v35 offset:46112
	s_waitcnt lgkmcnt(1)
	v_mfma_f32_32x32x16_bf16 v[2:17], v[76:79], v[88:91], v[2:17]
	ds_read_b128 v[76:79], v36 offset:32288
	v_mfma_f32_32x32x16_bf16 v[18:33], v[80:83], v[88:91], v[18:33]
	s_waitcnt lgkmcnt(1)
	v_mfma_f32_32x32x16_bf16 v[18:33], v[84:87], v[92:95], v[18:33]
	s_waitcnt lgkmcnt(0)
	v_mfma_f32_32x32x16_bf16 v[2:17], v[76:79], v[92:95], v[2:17]
	ds_read_b128 v[76:79], v36 offset:27712
	ds_read_b128 v[80:83], v36 offset:32320
	ds_read_b128 v[84:87], v35 offset:46144
	s_waitcnt lgkmcnt(0)
	v_mfma_f32_32x32x16_bf16 v[18:33], v[76:79], v[84:87], v[18:33]
	v_mfma_f32_32x32x16_bf16 v[2:17], v[80:83], v[84:87], v[2:17]
	ds_read_b128 v[76:79], v36 offset:27744
	ds_read_b128 v[80:83], v36 offset:32352
	ds_read_b128 v[84:87], v35 offset:46176
	s_waitcnt lgkmcnt(0)
	s_barrier
	s_waitcnt vmcnt(5)
	ds_write_b128 v34, v[52:55] offset:27648
	s_waitcnt vmcnt(4)
	ds_write_b128 v34, v[56:59] offset:32256
	s_waitcnt vmcnt(3)
	ds_write_b128 v34, v[60:63] offset:36864
	s_waitcnt vmcnt(2)
	ds_write_b128 v34, v[64:67] offset:41472
	s_waitcnt vmcnt(1)
	ds_write_b128 v34, v[68:71] offset:46080
	s_waitcnt vmcnt(0)
	ds_write_b128 v34, v[72:75] offset:50688
	global_load_dwordx4 v[52:55], v[38:39], off offset:768
	global_load_dwordx4 v[56:59], v[40:41], off offset:768
	global_load_dwordx4 v[60:63], v[42:43], off offset:768
	global_load_dwordx4 v[64:67], v[44:45], off offset:768
	global_load_dwordx4 v[68:71], v[46:47], off offset:768
	global_load_dwordx4 v[72:75], v[48:49], off offset:768
	v_mfma_f32_32x32x16_bf16 v[2:17], v[80:83], v[84:87], v[2:17]
	v_mfma_f32_32x32x16_bf16 v[18:33], v[76:79], v[84:87], v[18:33]
	ds_read_b128 v[76:79], v36 offset:4608
	ds_read_b128 v[80:83], v36
	ds_read_b128 v[84:87], v36 offset:32
	ds_read_b128 v[88:91], v35 offset:18432
	ds_read_b128 v[92:95], v35 offset:18464
	s_waitcnt lgkmcnt(1)
	v_mfma_f32_32x32x16_bf16 v[2:17], v[76:79], v[88:91], v[2:17]
	ds_read_b128 v[76:79], v36 offset:4640
	v_mfma_f32_32x32x16_bf16 v[18:33], v[80:83], v[88:91], v[18:33]
	s_waitcnt lgkmcnt(1)
	v_mfma_f32_32x32x16_bf16 v[18:33], v[84:87], v[92:95], v[18:33]
	s_waitcnt lgkmcnt(0)
	v_mfma_f32_32x32x16_bf16 v[2:17], v[76:79], v[92:95], v[2:17]
	ds_read_b128 v[76:79], v36 offset:64
	ds_read_b128 v[80:83], v36 offset:4672
	ds_read_b128 v[84:87], v35 offset:18496
	s_waitcnt lgkmcnt(0)
	v_mfma_f32_32x32x16_bf16 v[18:33], v[76:79], v[84:87], v[18:33]
	v_mfma_f32_32x32x16_bf16 v[2:17], v[80:83], v[84:87], v[2:17]
	ds_read_b128 v[76:79], v36 offset:96
	ds_read_b128 v[80:83], v36 offset:4704
	ds_read_b128 v[84:87], v35 offset:18528
	s_waitcnt lgkmcnt(0)
	s_barrier
; #define MFMA32(a, b, c) __builtin_amdgcn_mfma_f32_32x32x16_bf16((a), (b), (c), 0, 0, 0)
; #define GEMM_LOADG(kk) { const int ka_ = amode ? (((kk) >> 6) * 96) : (kk); \
;     _Pragma("unroll") for (int i = 0; i < 4; ++i) ra[i] = *(const u32x4*)(A + (size_t)(lr + 32 * i) * lda + ka_ + lk); \
;     _Pragma("unroll") for (int i = 0; i < 2 * NT; ++i) rb[i] = *(const u32x4*)(Bt + (size_t)(lr + 32 * i) * ldb + (kk) + lk); }
; #define GEMM_STORES(buf) { u16* As_ = S + (buf) * TILE; u16* Bs_ = As_ + 128 * LS; \
;     _Pragma("unroll") for (int i = 0; i < 4; ++i) *(u32x4*)(As_ + (lr + 32 * i) * LS + lk) = ra[i]; \
;     _Pragma("unroll") for (int i = 0; i < 2 * NT; ++i) *(u32x4*)(Bs_ + (lr + 32 * i) * LS + lk) = rb[i]; }
; template <int NT>
; DI void gemm_main_np(f32x16 (&acc)[2][NT], const u16* __restrict__ A, int lda, int amode, const u16* __restrict__ Bt,
;                   int ldb, int K, char* smem) {
;     ...
;   for (int k0 = 0; k0 < K; k0 += 64) {
;     const int cur = (k0 >> 6) & 1;
;     if (k0 + 64 < K) {
;       GEMM_STORES(cur ^ 1)
;       if (k0 + 128 < K) GEMM_LOADG(k0 + 128)
;     }
;     const u16* As = S + cur * TILE;
;     const u16* Bs = As + 128 * LS;
; #pragma unroll
;     for (int s = 0; s < 4; ++s) {
;       bf16x8 a[2], b[NT];
; #pragma unroll
;       for (int i = 0; i < 2; ++i) a[i] = *(const bf16x8*)(As + (wm * 64 + i * 32 + l31) * LS + s * 16 + hh * 8);
; #pragma unroll
;       for (int j = 0; j < NT; ++j) b[j] = *(const bf16x8*)(Bs + (wn * 32 * NT + j * 32 + l31) * LS + s * 16 + hh * 8);
; #pragma unroll
;       for (int i = 0; i < 2; ++i)
; #pragma unroll
;         for (int j = 0; j < NT; ++j) acc[i][j] = MFMA32(a[i], b[j], acc[i][j]);
;     }
	s_waitcnt vmcnt(5)
	ds_write_b128 v34, v[52:55]
	s_waitcnt vmcnt(4)
	ds_write_b128 v34, v[56:59] offset:4608
	s_waitcnt vmcnt(3)
	ds_write_b128 v34, v[60:63] offset:9216
	s_waitcnt vmcnt(2)
	ds_write_b128 v34, v[64:67] offset:13824
	s_waitcnt vmcnt(1)
	ds_write_b128 v34, v[68:71] offset:18432
	s_waitcnt vmcnt(0)
	ds_write_b128 v34, v[72:75] offset:23040
	global_load_dwordx4 v[52:55], v[38:39], off offset:896
	global_load_dwordx4 v[56:59], v[40:41], off offset:896
	global_load_dwordx4 v[60:63], v[42:43], off offset:896
	global_load_dwordx4 v[64:67], v[44:45], off offset:896
	global_load_dwordx4 v[68:71], v[46:47], off offset:896
	global_load_dwordx4 v[72:75], v[48:49], off offset:896
	v_mfma_f32_32x32x16_bf16 v[2:17], v[80:83], v[84:87], v[2:17]
	v_mfma_f32_32x32x16_bf16 v[18:33], v[76:79], v[84:87], v[18:33]
	ds_read_b128 v[76:79], v36 offset:32256
	ds_read_b128 v[80:83], v36 offset:27648
	ds_read_b128 v[84:87], v36 offset:27680
	ds_read_b128 v[88:91], v35 offset:46080
	ds_read_b128 v[92:95], v35 offset:46112
	s_waitcnt lgkmcnt(1)
	v_mfma_f32_32x32x16_bf16 v[2:17], v[76:79], v[88:91], v[2:17]
	ds_read_b128 v[76:79], v36 offset:32288
	v_mfma_f32_32x32x16_bf16 v[18:33], v[80:83], v[88:91], v[18:33]
	s_waitcnt lgkmcnt(1)
	v_mfma_f32_32x32x16_bf16 v[18:33], v[84:87], v[92:95], v[18:33]
	s_waitcnt lgkmcnt(0)
	v_mfma_f32_32x32x16_bf16 v[2:17], v[76:79], v[92:95], v[2:17]
	ds_read_b128 v[76:79], v36 offset:27712
	ds_read_b128 v[80:83], v36 offset:32320
	ds_read_b128 v[84:87], v35 offset:46144
	s_waitcnt lgkmcnt(0)
	v_mfma_f32_32x32x16_bf16 v[18:33], v[76:79], v[84:87], v[18:33]
	v_mfma_f32_32x32x16_bf16 v[2:17], v[80:83], v[84:87], v[2:17]
	ds_read_b128 v[76:79], v36 offset:27744
	ds_read_b128 v[80:83], v36 offset:32352
	ds_read_b128 v[84:87], v35 offset:46176
	s_waitcnt lgkmcnt(0)
	s_barrier
	s_waitcnt vmcnt(5)
	ds_write_b128 v34, v[52:55] offset:27648
	s_waitcnt vmcnt(4)
	ds_write_b128 v34, v[56:59] offset:32256
	s_waitcnt vmcnt(3)
	ds_write_b128 v34, v[60:63] offset:36864
	s_waitcnt vmcnt(2)
	ds_write_b128 v34, v[64:67] offset:41472
	s_waitcnt vmcnt(1)
	ds_write_b128 v34, v[68:71] offset:46080
	s_waitcnt vmcnt(0)
	ds_write_b128 v34, v[72:75] offset:50688
	global_load_dwordx4 v[52:55], v[38:39], off offset:1024
	global_load_dwordx4 v[56:59], v[40:41], off offset:1024
	global_load_dwordx4 v[60:63], v[42:43], off offset:1024
	global_load_dwordx4 v[64:67], v[44:45], off offset:1024
	global_load_dwordx4 v[68:71], v[46:47], off offset:1024
	global_load_dwordx4 v[72:75], v[48:49], off offset:1024
	v_mfma_f32_32x32x16_bf16 v[2:17], v[80:83], v[84:87], v[2:17]
	v_mfma_f32_32x32x16_bf16 v[18:33], v[76:79], v[84:87], v[18:33]
	ds_read_b128 v[76:79], v36 offset:4608
	ds_read_b128 v[80:83], v36
	ds_read_b128 v[84:87], v36 offset:32
	ds_read_b128 v[88:91], v35 offset:18432
	ds_read_b128 v[92:95], v35 offset:18464
	s_waitcnt lgkmcnt(1)
	v_mfma_f32_32x32x16_bf16 v[2:17], v[76:79], v[88:91], v[2:17]
	ds_read_b128 v[76:79], v36 offset:4640
	v_mfma_f32_32x32x16_bf16 v[18:33], v[80:83], v[88:91], v[18:33]
	s_waitcnt lgkmcnt(1)
	v_mfma_f32_32x32x16_bf16 v[18:33], v[84:87], v[92:95], v[18:33]
	s_waitcnt lgkmcnt(0)
	v_mfma_f32_32x32x16_bf16 v[2:17], v[76:79], v[92:95], v[2:17]
	ds_read_b128 v[76:79], v36 offset:64
	ds_read_b128 v[80:83], v36 offset:4672
	ds_read_b128 v[84:87], v35 offset:18496
	s_waitcnt lgkmcnt(0)
	v_mfma_f32_32x32x16_bf16 v[18:33], v[76:79], v[84:87], v[18:33]
	v_mfma_f32_32x32x16_bf16 v[2:17], v[80:83], v[84:87], v[2:17]
	ds_read_b128 v[76:79], v36 offset:96
	ds_read_b128 v[80:83], v36 offset:4704
	ds_read_b128 v[84:87], v35 offset:18528
	s_waitcnt lgkmcnt(0)
	s_barrier
	s_waitcnt vmcnt(5)
	ds_write_b128 v34, v[52:55]
	s_waitcnt vmcnt(4)
	ds_write_b128 v34, v[56:59] offset:4608
	s_waitcnt vmcnt(3)
	ds_write_b128 v34, v[60:63] offset:9216
	s_waitcnt vmcnt(2)
	ds_write_b128 v34, v[64:67] offset:13824
	s_waitcnt vmcnt(1)
	ds_write_b128 v34, v[68:71] offset:18432
	s_waitcnt vmcnt(0)
	ds_write_b128 v34, v[72:75] offset:23040
	global_load_dwordx4 v[52:55], v[38:39], off offset:1152
	global_load_dwordx4 v[56:59], v[40:41], off offset:1152
	global_load_dwordx4 v[60:63], v[42:43], off offset:1152
	global_load_dwordx4 v[64:67], v[44:45], off offset:1152
	global_load_dwordx4 v[68:71], v[46:47], off offset:1152
	global_load_dwordx4 v[72:75], v[48:49], off offset:1152
	v_mfma_f32_32x32x16_bf16 v[2:17], v[80:83], v[84:87], v[2:17]
	v_mfma_f32_32x32x16_bf16 v[18:33], v[76:79], v[84:87], v[18:33]
	ds_read_b128 v[76:79], v36 offset:32256
	ds_read_b128 v[80:83], v36 offset:27648
	ds_read_b128 v[84:87], v36 offset:27680
	ds_read_b128 v[88:91], v35 offset:46080
	ds_read_b128 v[92:95], v35 offset:46112
	s_waitcnt lgkmcnt(1)
	v_mfma_f32_32x32x16_bf16 v[2:17], v[76:79], v[88:91], v[2:17]
	ds_read_b128 v[76:79], v36 offset:32288
	v_mfma_f32_32x32x16_bf16 v[18:33], v[80:83], v[88:91], v[18:33]
	s_waitcnt lgkmcnt(1)
	v_mfma_f32_32x32x16_bf16 v[18:33], v[84:87], v[92:95], v[18:33]
	s_waitcnt lgkmcnt(0)
	v_mfma_f32_32x32x16_bf16 v[2:17], v[76:79], v[92:95], v[2:17]
	ds_read_b128 v[76:79], v36 offset:27712
	ds_read_b128 v[80:83], v36 offset:32320
	ds_read_b128 v[84:87], v35 offset:46144
	s_waitcnt lgkmcnt(0)
	v_mfma_f32_32x32x16_bf16 v[18:33], v[76:79], v[84:87], v[18:33]
	v_mfma_f32_32x32x16_bf16 v[2:17], v[80:83], v[84:87], v[2:17]
	ds_read_b128 v[76:79], v36 offset:27744
	ds_read_b128 v[80:83], v36 offset:32352
	ds_read_b128 v[84:87], v35 offset:46176
	s_waitcnt lgkmcnt(0)
	s_barrier
; #define MFMA32(a, b, c) __builtin_amdgcn_mfma_f32_32x32x16_bf16((a), (b), (c), 0, 0, 0)
; #define GEMM_LOADG(kk) { const int ka_ = amode ? (((kk) >> 6) * 96) : (kk); \
;     _Pragma("unroll") for (int i = 0; i < 4; ++i) ra[i] = *(const u32x4*)(A + (size_t)(lr + 32 * i) * lda + ka_ + lk); \
;     _Pragma("unroll") for (int i = 0; i < 2 * NT; ++i) rb[i] = *(const u32x4*)(Bt + (size_t)(lr + 32 * i) * ldb + (kk) + lk); }
; #define GEMM_STORES(buf) { u16* As_ = S + (buf) * TILE; u16* Bs_ = As_ + 128 * LS; \
;     _Pragma("unroll") for (int i = 0; i < 4; ++i) *(u32x4*)(As_ + (lr + 32 * i) * LS + lk) = ra[i]; \
;     _Pragma("unroll") for (int i = 0; i < 2 * NT; ++i) *(u32x4*)(Bs_ + (lr + 32 * i) * LS + lk) = rb[i]; }
; template <int NT>
; DI void gemm_main_np(f32x16 (&acc)[2][NT], const u16* __restrict__ A, int lda, int amode, const u16* __restrict__ Bt,
;                   int ldb, int K, char* smem) {
;     ...
;   for (int k0 = 0; k0 < K; k0 += 64) {
;     const int cur = (k0 >> 6) & 1;
;     if (k0 + 64 < K) {
;       GEMM_STORES(cur ^ 1)
;       if (k0 + 128 < K) GEMM_LOADG(k0 + 128)
;     }
;     const u16* As = S + cur * TILE;
;     const u16* Bs = As + 128 * LS;
; #pragma unroll
;     for (int s = 0; s < 4; ++s) {
;       bf16x8 a[2], b[NT];
; #pragma unroll
;       for (int i = 0; i < 2; ++i) a[i] = *(const bf16x8*)(As + (wm * 64 + i * 32 + l31) * LS + s * 16 + hh * 8);
; #pragma unroll
;       for (int j = 0; j < NT; ++j) b[j] = *(const bf16x8*)(Bs + (wn * 32 * NT + j * 32 + l31) * LS + s * 16 + hh * 8);
; #pragma unroll
;       for (int i = 0; i < 2; ++i)
; #pragma unroll
;         for (int j = 0; j < NT; ++j) acc[i][j] = MFMA32(a[i], b[j], acc[i][j]);
;     }
	s_waitcnt vmcnt(5)
	ds_write_b128 v34, v[52:55] offset:27648
	s_waitcnt vmcnt(4)
	ds_write_b128 v34, v[56:59] offset:32256
	s_waitcnt vmcnt(3)
	ds_write_b128 v34, v[60:63] offset:36864
	s_waitcnt vmcnt(2)
	ds_write_b128 v34, v[64:67] offset:41472
	s_waitcnt vmcnt(1)
	ds_write_b128 v34, v[68:71] offset:46080
	s_waitcnt vmcnt(0)
	ds_write_b128 v34, v[72:75] offset:50688
	global_load_dwordx4 v[52:55], v[38:39], off offset:1280
	global_load_dwordx4 v[56:59], v[40:41], off offset:1280
	global_load_dwordx4 v[60:63], v[42:43], off offset:1280
	global_load_dwordx4 v[64:67], v[44:45], off offset:1280
	global_load_dwordx4 v[68:71], v[46:47], off offset:1280
	global_load_dwordx4 v[72:75], v[48:49], off offset:1280
	v_mfma_f32_32x32x16_bf16 v[2:17], v[80:83], v[84:87], v[2:17]
	v_mfma_f32_32x32x16_bf16 v[18:33], v[76:79], v[84:87], v[18:33]
	ds_read_b128 v[76:79], v36 offset:4608
	ds_read_b128 v[80:83], v36
	ds_read_b128 v[84:87], v36 offset:32
	ds_read_b128 v[88:91], v35 offset:18432
	ds_read_b128 v[92:95], v35 offset:18464
	s_waitcnt lgkmcnt(1)
	v_mfma_f32_32x32x16_bf16 v[2:17], v[76:79], v[88:91], v[2:17]
	ds_read_b128 v[76:79], v36 offset:4640
	v_mfma_f32_32x32x16_bf16 v[18:33], v[80:83], v[88:91], v[18:33]
	s_waitcnt lgkmcnt(1)
	v_mfma_f32_32x32x16_bf16 v[18:33], v[84:87], v[92:95], v[18:33]
	s_waitcnt lgkmcnt(0)
	v_mfma_f32_32x32x16_bf16 v[2:17], v[76:79], v[92:95], v[2:17]
	ds_read_b128 v[76:79], v36 offset:64
	ds_read_b128 v[80:83], v36 offset:4672
	ds_read_b128 v[84:87], v35 offset:18496
	s_waitcnt lgkmcnt(0)
	v_mfma_f32_32x32x16_bf16 v[18:33], v[76:79], v[84:87], v[18:33]
	v_mfma_f32_32x32x16_bf16 v[2:17], v[80:83], v[84:87], v[2:17]
	ds_read_b128 v[76:79], v36 offset:96
	ds_read_b128 v[80:83], v36 offset:4704
	ds_read_b128 v[84:87], v35 offset:18528
	s_waitcnt lgkmcnt(0)
	s_barrier
	s_waitcnt vmcnt(5)
	ds_write_b128 v34, v[52:55]
	s_waitcnt vmcnt(4)
	ds_write_b128 v34, v[56:59] offset:4608
	s_waitcnt vmcnt(3)
	ds_write_b128 v34, v[60:63] offset:9216
	s_waitcnt vmcnt(2)
	ds_write_b128 v34, v[64:67] offset:13824
	s_waitcnt vmcnt(1)
	ds_write_b128 v34, v[68:71] offset:18432
	s_waitcnt vmcnt(0)
	ds_write_b128 v34, v[72:75] offset:23040
	global_load_dwordx4 v[52:55], v[38:39], off offset:1408
	global_load_dwordx4 v[56:59], v[40:41], off offset:1408
	global_load_dwordx4 v[60:63], v[42:43], off offset:1408
	global_load_dwordx4 v[64:67], v[44:45], off offset:1408
	global_load_dwordx4 v[68:71], v[46:47], off offset:1408
	global_load_dwordx4 v[72:75], v[48:49], off offset:1408
	v_mfma_f32_32x32x16_bf16 v[2:17], v[80:83], v[84:87], v[2:17]
	v_mfma_f32_32x32x16_bf16 v[18:33], v[76:79], v[84:87], v[18:33]
	ds_read_b128 v[76:79], v36 offset:32256
	ds_read_b128 v[80:83], v36 offset:27648
	ds_read_b128 v[84:87], v36 offset:27680
	ds_read_b128 v[88:91], v35 offset:46080
	ds_read_b128 v[92:95], v35 offset:46112
	s_waitcnt lgkmcnt(1)
	v_mfma_f32_32x32x16_bf16 v[2:17], v[76:79], v[88:91], v[2:17]
	ds_read_b128 v[76:79], v36 offset:32288
	v_mfma_f32_32x32x16_bf16 v[18:33], v[80:83], v[88:91], v[18:33]
	s_waitcnt lgkmcnt(1)
	v_mfma_f32_32x32x16_bf16 v[18:33], v[84:87], v[92:95], v[18:33]
	s_waitcnt lgkmcnt(0)
	v_mfma_f32_32x32x16_bf16 v[2:17], v[76:79], v[92:95], v[2:17]
	ds_read_b128 v[76:79], v36 offset:27712
	ds_read_b128 v[80:83], v36 offset:32320
	ds_read_b128 v[84:87], v35 offset:46144
	s_waitcnt lgkmcnt(0)
	v_mfma_f32_32x32x16_bf16 v[18:33], v[76:79], v[84:87], v[18:33]
	v_mfma_f32_32x32x16_bf16 v[2:17], v[80:83], v[84:87], v[2:17]
	ds_read_b128 v[76:79], v36 offset:27744
	ds_read_b128 v[80:83], v36 offset:32352
	ds_read_b128 v[84:87], v35 offset:46176
	s_waitcnt lgkmcnt(0)
	s_barrier
	s_waitcnt vmcnt(5)
	ds_write_b128 v34, v[52:55] offset:27648
	s_waitcnt vmcnt(4)
	ds_write_b128 v34, v[56:59] offset:32256
	s_waitcnt vmcnt(3)
	ds_write_b128 v34, v[60:63] offset:36864
	s_waitcnt vmcnt(2)
	ds_write_b128 v34, v[64:67] offset:41472
	s_waitcnt vmcnt(1)
	ds_write_b128 v34, v[68:71] offset:46080
	s_waitcnt vmcnt(0)
	ds_write_b128 v34, v[72:75] offset:50688
	global_load_dwordx4 v[52:55], v[38:39], off offset:1536
	global_load_dwordx4 v[56:59], v[40:41], off offset:1536
	global_load_dwordx4 v[60:63], v[42:43], off offset:1536
	global_load_dwordx4 v[64:67], v[44:45], off offset:1536
	global_load_dwordx4 v[68:71], v[46:47], off offset:1536
	global_load_dwordx4 v[72:75], v[48:49], off offset:1536
	v_mfma_f32_32x32x16_bf16 v[2:17], v[80:83], v[84:87], v[2:17]
	v_mfma_f32_32x32x16_bf16 v[18:33], v[76:79], v[84:87], v[18:33]
	ds_read_b128 v[76:79], v36 offset:4608
	ds_read_b128 v[80:83], v36
	ds_read_b128 v[84:87], v36 offset:32
	ds_read_b128 v[88:91], v35 offset:18432
	ds_read_b128 v[92:95], v35 offset:18464
	s_waitcnt lgkmcnt(1)
	v_mfma_f32_32x32x16_bf16 v[2:17], v[76:79], v[88:91], v[2:17]
	ds_read_b128 v[76:79], v36 offset:4640
	v_mfma_f32_32x32x16_bf16 v[18:33], v[80:83], v[88:91], v[18:33]
	s_waitcnt lgkmcnt(1)
	v_mfma_f32_32x32x16_bf16 v[18:33], v[84:87], v[92:95], v[18:33]
	s_waitcnt lgkmcnt(0)
	v_mfma_f32_32x32x16_bf16 v[2:17], v[76:79], v[92:95], v[2:17]
	ds_read_b128 v[76:79], v36 offset:64
	ds_read_b128 v[80:83], v36 offset:4672
	ds_read_b128 v[84:87], v35 offset:18496
	s_waitcnt lgkmcnt(0)
	v_mfma_f32_32x32x16_bf16 v[18:33], v[76:79], v[84:87], v[18:33]
	v_mfma_f32_32x32x16_bf16 v[2:17], v[80:83], v[84:87], v[2:17]
	ds_read_b128 v[76:79], v36 offset:96
	ds_read_b128 v[80:83], v36 offset:4704
	ds_read_b128 v[84:87], v35 offset:18528
	s_waitcnt lgkmcnt(0)
	s_barrier
; #define MFMA32(a, b, c) __builtin_amdgcn_mfma_f32_32x32x16_bf16((a), (b), (c), 0, 0, 0)
; #define GEMM_LOADG(kk) { const int ka_ = amode ? (((kk) >> 6) * 96) : (kk); \
;     _Pragma("unroll") for (int i = 0; i < 4; ++i) ra[i] = *(const u32x4*)(A + (size_t)(lr + 32 * i) * lda + ka_ + lk); \
;     _Pragma("unroll") for (int i = 0; i < 2 * NT; ++i) rb[i] = *(const u32x4*)(Bt + (size_t)(lr + 32 * i) * ldb + (kk) + lk); }
; #define GEMM_STORES(buf) { u16* As_ = S + (buf) * TILE; u16* Bs_ = As_ + 128 * LS; \
;     _Pragma("unroll") for (int i = 0; i < 4; ++i) *(u32x4*)(As_ + (lr + 32 * i) * LS + lk) = ra[i]; \
;     _Pragma("unroll") for (int i = 0; i < 2 * NT; ++i) *(u32x4*)(Bs_ + (lr + 32 * i) * LS + lk) = rb[i]; }
; template <int NT>
; DI void gemm_main_np(f32x16 (&acc)[2][NT], const u16* __restrict__ A, int lda, int amode, const u16* __restrict__ Bt,
;                   int ldb, int K, char* smem) {
;     ...
;   for (int k0 = 0; k0 < K; k0 += 64) {
;     const int cur = (k0 >> 6) & 1;
;     if (k0 + 64 < K) {
;       GEMM_STORES(cur ^ 1)
;       if (k0 + 128 < K) GEMM_LOADG(k0 + 128)
;     }
;     const u16* As = S + cur * TILE;
;     const u16* Bs = As + 128 * LS;
; #pragma unroll
;     for (int s = 0; s < 4; ++s) {
;       bf16x8 a[2], b[NT];
; #pragma unroll
;       for (int i = 0; i < 2; ++i) a[i] = *(const bf16x8*)(As + (wm * 64 + i * 32 + l31) * LS + s * 16 + hh * 8);
; #pragma unroll
;       for (int j = 0; j < NT; ++j) b[j] = *(const bf16x8*)(Bs + (wn * 32 * NT + j * 32 + l31) * LS + s * 16 + hh * 8);
; #pragma unroll
;       for (int i = 0; i < 2; ++i)
; #pragma unroll
;         for (int j = 0; j < NT; ++j) acc[i][j] = MFMA32(a[i], b[j], acc[i][j]);
;     }
	s_waitcnt vmcnt(5)
	ds_write_b128 v34, v[52:55]
	s_waitcnt vmcnt(4)
	ds_write_b128 v34, v[56:59] offset:4608
	s_waitcnt vmcnt(3)
	ds_write_b128 v34, v[60:63] offset:9216
	s_waitcnt vmcnt(2)
	ds_write_b128 v34, v[64:67] offset:13824
	s_waitcnt vmcnt(1)
	ds_write_b128 v34, v[68:71] offset:18432
	s_waitcnt vmcnt(0)
	ds_write_b128 v34, v[72:75] offset:23040
	global_load_dwordx4 v[52:55], v[38:39], off offset:1664
	global_load_dwordx4 v[56:59], v[40:41], off offset:1664
	global_load_dwordx4 v[60:63], v[42:43], off offset:1664
	global_load_dwordx4 v[64:67], v[44:45], off offset:1664
	global_load_dwordx4 v[68:71], v[46:47], off offset:1664
	global_load_dwordx4 v[72:75], v[48:49], off offset:1664
	v_mfma_f32_32x32x16_bf16 v[2:17], v[80:83], v[84:87], v[2:17]
	v_mfma_f32_32x32x16_bf16 v[18:33], v[76:79], v[84:87], v[18:33]
	ds_read_b128 v[76:79], v36 offset:32256
	ds_read_b128 v[80:83], v36 offset:27648
	ds_read_b128 v[84:87], v36 offset:27680
	ds_read_b128 v[88:91], v35 offset:46080
	ds_read_b128 v[92:95], v35 offset:46112
	s_waitcnt lgkmcnt(1)
	v_mfma_f32_32x32x16_bf16 v[2:17], v[76:79], v[88:91], v[2:17]
	ds_read_b128 v[76:79], v36 offset:32288
	v_mfma_f32_32x32x16_bf16 v[18:33], v[80:83], v[88:91], v[18:33]
	s_waitcnt lgkmcnt(1)
	v_mfma_f32_32x32x16_bf16 v[18:33], v[84:87], v[92:95], v[18:33]
	s_waitcnt lgkmcnt(0)
	v_mfma_f32_32x32x16_bf16 v[2:17], v[76:79], v[92:95], v[2:17]
	ds_read_b128 v[76:79], v36 offset:27712
	ds_read_b128 v[80:83], v36 offset:32320
	ds_read_b128 v[84:87], v35 offset:46144
	s_waitcnt lgkmcnt(0)
	v_mfma_f32_32x32x16_bf16 v[18:33], v[76:79], v[84:87], v[18:33]
	v_mfma_f32_32x32x16_bf16 v[2:17], v[80:83], v[84:87], v[2:17]
	ds_read_b128 v[76:79], v36 offset:27744
	ds_read_b128 v[80:83], v36 offset:32352
	ds_read_b128 v[84:87], v35 offset:46176
	s_waitcnt lgkmcnt(0)
	s_barrier
	s_waitcnt vmcnt(5)
	ds_write_b128 v34, v[52:55] offset:27648
	s_waitcnt vmcnt(4)
	ds_write_b128 v34, v[56:59] offset:32256
	s_waitcnt vmcnt(3)
	ds_write_b128 v34, v[60:63] offset:36864
	s_waitcnt vmcnt(2)
	ds_write_b128 v34, v[64:67] offset:41472
	s_waitcnt vmcnt(1)
	ds_write_b128 v34, v[68:71] offset:46080
	s_waitcnt vmcnt(0)
	ds_write_b128 v34, v[72:75] offset:50688
	global_load_dwordx4 v[52:55], v[38:39], off offset:1792
	global_load_dwordx4 v[56:59], v[40:41], off offset:1792
	global_load_dwordx4 v[60:63], v[42:43], off offset:1792
	global_load_dwordx4 v[64:67], v[44:45], off offset:1792
	global_load_dwordx4 v[68:71], v[46:47], off offset:1792
	global_load_dwordx4 v[72:75], v[48:49], off offset:1792
	v_mfma_f32_32x32x16_bf16 v[2:17], v[80:83], v[84:87], v[2:17]
	v_mfma_f32_32x32x16_bf16 v[18:33], v[76:79], v[84:87], v[18:33]
	ds_read_b128 v[76:79], v36 offset:4608
	ds_read_b128 v[80:83], v36
	ds_read_b128 v[84:87], v36 offset:32
	ds_read_b128 v[88:91], v35 offset:18432
	ds_read_b128 v[92:95], v35 offset:18464
	s_waitcnt lgkmcnt(1)
	v_mfma_f32_32x32x16_bf16 v[2:17], v[76:79], v[88:91], v[2:17]
	ds_read_b128 v[76:79], v36 offset:4640
	v_mfma_f32_32x32x16_bf16 v[18:33], v[80:83], v[88:91], v[18:33]
	s_waitcnt lgkmcnt(1)
	v_mfma_f32_32x32x16_bf16 v[18:33], v[84:87], v[92:95], v[18:33]
	s_waitcnt lgkmcnt(0)
	v_mfma_f32_32x32x16_bf16 v[2:17], v[76:79], v[92:95], v[2:17]
	ds_read_b128 v[76:79], v36 offset:64
	ds_read_b128 v[80:83], v36 offset:4672
	ds_read_b128 v[84:87], v35 offset:18496
	s_waitcnt lgkmcnt(0)
	v_mfma_f32_32x32x16_bf16 v[18:33], v[76:79], v[84:87], v[18:33]
	v_mfma_f32_32x32x16_bf16 v[2:17], v[80:83], v[84:87], v[2:17]
	ds_read_b128 v[76:79], v36 offset:96
	ds_read_b128 v[80:83], v36 offset:4704
	ds_read_b128 v[84:87], v35 offset:18528
	s_waitcnt lgkmcnt(0)
	s_barrier
	s_waitcnt vmcnt(5)
	ds_write_b128 v34, v[52:55]
	s_waitcnt vmcnt(4)
	ds_write_b128 v34, v[56:59] offset:4608
	s_waitcnt vmcnt(3)
	ds_write_b128 v34, v[60:63] offset:9216
	s_waitcnt vmcnt(2)
	ds_write_b128 v34, v[64:67] offset:13824
	s_waitcnt vmcnt(1)
	ds_write_b128 v34, v[68:71] offset:18432
	s_waitcnt vmcnt(0)
	ds_write_b128 v34, v[72:75] offset:23040
	global_load_dwordx4 v[52:55], v[38:39], off offset:1920
	s_nop 0
	global_load_dwordx4 v[38:41], v[40:41], off offset:1920
	s_nop 0
	global_load_dwordx4 v[56:59], v[42:43], off offset:1920
	s_nop 0
	global_load_dwordx4 v[42:45], v[44:45], off offset:1920
	s_nop 0
	global_load_dwordx4 v[60:63], v[46:47], off offset:1920
	s_nop 0
	global_load_dwordx4 v[46:49], v[48:49], off offset:1920
	v_mfma_f32_32x32x16_bf16 v[2:17], v[80:83], v[84:87], v[2:17]
	v_mfma_f32_32x32x16_bf16 v[18:33], v[76:79], v[84:87], v[18:33]
	ds_read_b128 v[64:67], v36 offset:32256
	ds_read_b128 v[68:71], v36 offset:27648
	ds_read_b128 v[72:75], v36 offset:27680
	ds_read_b128 v[76:79], v35 offset:46080
	ds_read_b128 v[80:83], v35 offset:46112
	s_waitcnt lgkmcnt(1)
	v_mfma_f32_32x32x16_bf16 v[2:17], v[64:67], v[76:79], v[2:17]
	ds_read_b128 v[64:67], v36 offset:32288
	v_mfma_f32_32x32x16_bf16 v[18:33], v[68:71], v[76:79], v[18:33]
	s_waitcnt lgkmcnt(0)
	v_mfma_f32_32x32x16_bf16 v[2:17], v[64:67], v[80:83], v[2:17]
	v_mfma_f32_32x32x16_bf16 v[18:33], v[72:75], v[80:83], v[18:33]
	ds_read_b128 v[64:67], v36 offset:27712
	ds_read_b128 v[68:71], v36 offset:32320
	ds_read_b128 v[72:75], v35 offset:46144
	s_waitcnt lgkmcnt(0)
	v_mfma_f32_32x32x16_bf16 v[2:17], v[68:71], v[72:75], v[2:17]
	v_mfma_f32_32x32x16_bf16 v[18:33], v[64:67], v[72:75], v[18:33]
	ds_read_b128 v[64:67], v36 offset:27744
	ds_read_b128 v[68:71], v36 offset:32352
	ds_read_b128 v[72:75], v35 offset:46176
	s_waitcnt lgkmcnt(0)
	s_barrier
; #define MFMA32(a, b, c) __builtin_amdgcn_mfma_f32_32x32x16_bf16((a), (b), (c), 0, 0, 0)
; #define GEMM_LOADG(kk) { const int ka_ = amode ? (((kk) >> 6) * 96) : (kk); \
;     _Pragma("unroll") for (int i = 0; i < 4; ++i) ra[i] = *(const u32x4*)(A + (size_t)(lr + 32 * i) * lda + ka_ + lk); \
;     _Pragma("unroll") for (int i = 0; i < 2 * NT; ++i) rb[i] = *(const u32x4*)(Bt + (size_t)(lr + 32 * i) * ldb + (kk) + lk); }
; #define GEMM_STORES(buf) { u16* As_ = S + (buf) * TILE; u16* Bs_ = As_ + 128 * LS; \
;     _Pragma("unroll") for (int i = 0; i < 4; ++i) *(u32x4*)(As_ + (lr + 32 * i) * LS + lk) = ra[i]; \
;     _Pragma("unroll") for (int i = 0; i < 2 * NT; ++i) *(u32x4*)(Bs_ + (lr + 32 * i) * LS + lk) = rb[i]; }
; template <int NT>
; DI void gemm_main_np(f32x16 (&acc)[2][NT], const u16* __restrict__ A, int lda, int amode, const u16* __restrict__ Bt,
;                   int ldb, int K, char* smem) {
;     ...
;   for (int k0 = 0; k0 < K; k0 += 64) {
;     const int cur = (k0 >> 6) & 1;
;     if (k0 + 64 < K) {
;       GEMM_STORES(cur ^ 1)
;       if (k0 + 128 < K) GEMM_LOADG(k0 + 128)
;     }
;     const u16* As = S + cur * TILE;
;     const u16* Bs = As + 128 * LS;
; #pragma unroll
;     for (int s = 0; s < 4; ++s) {
;       bf16x8 a[2], b[NT];
; #pragma unroll
;       for (int i = 0; i < 2; ++i) a[i] = *(const bf16x8*)(As + (wm * 64 + i * 32 + l31) * LS + s * 16 + hh * 8);
; #pragma unroll
;       for (int j = 0; j < NT; ++j) b[j] = *(const bf16x8*)(Bs + (wn * 32 * NT + j * 32 + l31) * LS + s * 16 + hh * 8);
; #pragma unroll
;       for (int i = 0; i < 2; ++i)
; #pragma unroll
;         for (int j = 0; j < NT; ++j) acc[i][j] = MFMA32(a[i], b[j], acc[i][j]);
;     }
;     __syncthreads();
;   }
	s_waitcnt vmcnt(5)
	ds_write_b128 v34, v[52:55] offset:27648
	s_waitcnt vmcnt(4)
	ds_write_b128 v34, v[38:41] offset:32256
	s_waitcnt vmcnt(3)
	ds_write_b128 v34, v[56:59] offset:36864
	s_waitcnt vmcnt(2)
	ds_write_b128 v34, v[42:45] offset:41472
	s_waitcnt vmcnt(1)
	ds_write_b128 v34, v[60:63] offset:46080
	s_waitcnt vmcnt(0)
	ds_write_b128 v34, v[46:49] offset:50688
	v_mfma_f32_32x32x16_bf16 v[2:17], v[68:71], v[72:75], v[2:17]
	ds_read_b128 v[38:41], v36 offset:4608
	ds_read_b128 v[42:45], v36
	ds_read_b128 v[46:49], v36 offset:32
	ds_read_b128 v[52:55], v35 offset:18432
	ds_read_b128 v[56:59], v35 offset:18464
	v_mfma_f32_32x32x16_bf16 v[18:33], v[64:67], v[72:75], v[18:33]
	s_waitcnt lgkmcnt(1)
	v_mfma_f32_32x32x16_bf16 v[2:17], v[38:41], v[52:55], v[2:17]
	ds_read_b128 v[38:41], v36 offset:4640
	v_mfma_f32_32x32x16_bf16 v[18:33], v[42:45], v[52:55], v[18:33]
	s_waitcnt lgkmcnt(1)
	v_mfma_f32_32x32x16_bf16 v[18:33], v[46:49], v[56:59], v[18:33]
	s_waitcnt lgkmcnt(0)
	v_mfma_f32_32x32x16_bf16 v[2:17], v[38:41], v[56:59], v[2:17]
	ds_read_b128 v[38:41], v36 offset:64
	ds_read_b128 v[42:45], v36 offset:4672
	ds_read_b128 v[46:49], v35 offset:18496
	s_waitcnt lgkmcnt(0)
	v_mfma_f32_32x32x16_bf16 v[18:33], v[38:41], v[46:49], v[18:33]
	v_mfma_f32_32x32x16_bf16 v[2:17], v[42:45], v[46:49], v[2:17]
	ds_read_b128 v[38:41], v36 offset:96
	ds_read_b128 v[42:45], v36 offset:4704
	ds_read_b128 v[46:49], v35 offset:18528
	s_waitcnt lgkmcnt(0)
	s_barrier
	v_mfma_f32_32x32x16_bf16 v[18:33], v[38:41], v[46:49], v[18:33]
	v_mfma_f32_32x32x16_bf16 v[2:17], v[42:45], v[46:49], v[2:17]
	ds_read_b128 v[38:41], v35 offset:46176
	ds_read_b128 v[42:45], v36 offset:32352
	ds_read_b128 v[46:49], v36 offset:27744
	ds_read_b128 v[52:55], v35 offset:46144
	ds_read_b128 v[56:59], v36 offset:32320
	ds_read_b128 v[60:63], v36 offset:27712
	ds_read_b128 v[64:67], v35 offset:46080
	ds_read_b128 v[68:71], v35 offset:46112
	ds_read_b128 v[72:75], v36 offset:32288
	ds_read_b128 v[76:79], v36 offset:27648
	ds_read_b128 v[80:83], v36 offset:27680
	ds_read_b128 v[34:37], v36 offset:32256
	s_waitcnt lgkmcnt(0)
	s_barrier
; DI int crow(int r, int hh) { return (r & 3) + 8 * (r >> 2) + 4 * hh; }
; DI void resid_ctx_half(KP p, int l, int u, int which, const u16* A, int K, const u16* Wt, const float* xin, float* xout, char* smem) {
;     ...
;   const float* gate = (const float*)(p->ws + OFF_MODS) + (size_t)(l * 5 + 4) * 6144 + which * 3072 + 2048;
; #pragma unroll
;   for (int i = 0; i < 2; ++i) {
;     const int mrow0 = (mt - 128) * 128 + wm * 64 + i * 32, n = nt * 64 + wn * 32 + l31;
;     const float gv = gate[n];
; #pragma unroll
;     for (int r = 0; r < 16; ++r) {
;       const size_t o = (size_t)(mrow0 + crow(r, hh)) * 1024 + n;
;       xout[o] = xin[o] + gv * acc[i][0][r];
;     }
;   }
	s_load_dwordx2 s[4:5], s[14:15], 0x130
	s_waitcnt lgkmcnt(0)
	s_add_u32 s4, s4, s10
	v_mfma_f32_32x32x16_bf16 v[18:33], v[76:79], v[64:67], v[18:33]
	s_addc_u32 s5, s5, s11
	v_mfma_f32_32x32x16_bf16 v[2:17], v[34:37], v[64:67], v[2:17]
	v_lshrrev_b32_e32 v36, 1, v51
	v_and_b32_e32 v34, 31, v50
	v_and_b32_e32 v36, 32, v36
	v_or3_b32 v34, v34, v36, s3
	v_ashrrev_i32_e32 v35, 1, v51
	v_lshlrev_b32_e32 v198, 2, v34
	v_lshrrev_b32_e32 v34, 3, v50
	v_mfma_f32_32x32x16_bf16 v[18:33], v[80:83], v[68:71], v[18:33]
	v_and_b32_e32 v35, 0xffffffc0, v35
	v_and_or_b32 v34, v34, 4, s2
	v_add_u32_e32 v34, v34, v35
	v_ashrrev_i32_e32 v35, 31, v34
	v_lshl_add_u64 v[36:37], s[4:5], 0, v[198:199]
	s_mov_b32 s2, 0xe83a000
	v_add_co_u32_e32 v36, vcc, s2, v36
	v_mfma_f32_32x32x16_bf16 v[2:17], v[72:75], v[68:71], v[2:17]
	s_nop 0
	v_addc_co_u32_e32 v37, vcc, 0, v37, vcc
	v_mfma_f32_32x32x16_bf16 v[18:33], v[60:63], v[52:55], v[18:33]
	v_mfma_f32_32x32x16_bf16 v[2:17], v[56:59], v[52:55], v[2:17]
	v_mfma_f32_32x32x16_bf16 v[18:33], v[46:49], v[38:41], v[18:33]
	v_mfma_f32_32x32x16_bf16 v[2:17], v[42:45], v[38:41], v[2:17]
	global_load_dword v38, v[36:37], off
	v_lshl_or_b32 v196, v34, 12, v198
	v_mov_b32_e32 v132, v196
	v_add_u32_e32 v133, 0x1000, v196
	v_add_u32_e32 v134, 0x2000, v196
	v_add_u32_e32 v135, 0x3000, v196
	v_add_u32_e32 v136, 0x8000, v196
	v_add_u32_e32 v137, 0x9000, v196
	v_add_u32_e32 v138, 0xa000, v196
	v_add_u32_e32 v139, 0xb000, v196
	v_add_u32_e32 v140, 0x10000, v196
	v_add_u32_e32 v141, 0x11000, v196
	v_add_u32_e32 v142, 0x12000, v196
	v_add_u32_e32 v143, 0x13000, v196
	v_add_u32_e32 v144, 0x18000, v196
	v_add_u32_e32 v145, 0x19000, v196
	v_add_u32_e32 v146, 0x1a000, v196
	v_add_u32_e32 v147, 0x1b000, v196
	v_add_u32_e32 v148, 0x20000, v196
	v_add_u32_e32 v149, 0x21000, v196
	v_add_u32_e32 v150, 0x22000, v196
	v_add_u32_e32 v151, 0x23000, v196
	v_add_u32_e32 v152, 0x28000, v196
	v_add_u32_e32 v153, 0x29000, v196
	v_add_u32_e32 v154, 0x2a000, v196
	v_add_u32_e32 v155, 0x2b000, v196
	v_add_u32_e32 v156, 0x30000, v196
	v_add_u32_e32 v157, 0x31000, v196
	v_add_u32_e32 v158, 0x32000, v196
	v_add_u32_e32 v159, 0x33000, v196
	v_add_u32_e32 v160, 0x38000, v196
	v_add_u32_e32 v161, 0x39000, v196
	v_add_u32_e32 v162, 0x3a000, v196
	v_add_u32_e32 v163, 0x3b000, v196
	global_load_dword v164, v132, s[12:13]
	global_load_dword v165, v133, s[12:13]
	global_load_dword v166, v134, s[12:13]
	global_load_dword v167, v135, s[12:13]
	global_load_dword v168, v136, s[12:13]
	global_load_dword v169, v137, s[12:13]
	global_load_dword v170, v138, s[12:13]
	global_load_dword v171, v139, s[12:13]
	global_load_dword v172, v140, s[12:13]
	global_load_dword v173, v141, s[12:13]
	global_load_dword v174, v142, s[12:13]
	global_load_dword v175, v143, s[12:13]
	global_load_dword v176, v144, s[12:13]
	global_load_dword v177, v145, s[12:13]
	global_load_dword v178, v146, s[12:13]
	global_load_dword v179, v147, s[12:13]
	global_load_dword v180, v148, s[12:13]
	global_load_dword v181, v149, s[12:13]
	global_load_dword v182, v150, s[12:13]
	global_load_dword v183, v151, s[12:13]
	global_load_dword v184, v152, s[12:13]
	global_load_dword v185, v153, s[12:13]
	global_load_dword v186, v154, s[12:13]
	global_load_dword v187, v155, s[12:13]
	global_load_dword v188, v156, s[12:13]
	global_load_dword v189, v157, s[12:13]
	global_load_dword v190, v158, s[12:13]
	global_load_dword v191, v159, s[12:13]
	global_load_dword v192, v160, s[12:13]
	global_load_dword v193, v161, s[12:13]
	global_load_dword v194, v162, s[12:13]
	global_load_dword v195, v163, s[12:13]
	s_waitcnt vmcnt(31)
	v_fma_f32 v18, v18, v38, v164
	global_store_dword v132, v18, s[16:17]
	s_waitcnt vmcnt(31)
	v_fma_f32 v19, v19, v38, v165
	global_store_dword v133, v19, s[16:17]
	s_waitcnt vmcnt(31)
	v_fma_f32 v20, v20, v38, v166
	global_store_dword v134, v20, s[16:17]
	s_waitcnt vmcnt(31)
	v_fma_f32 v21, v21, v38, v167
	global_store_dword v135, v21, s[16:17]
	s_waitcnt vmcnt(31)
	v_fma_f32 v22, v22, v38, v168
	global_store_dword v136, v22, s[16:17]
	s_waitcnt vmcnt(31)
	v_fma_f32 v23, v23, v38, v169
	global_store_dword v137, v23, s[16:17]
	s_waitcnt vmcnt(31)
	v_fma_f32 v24, v24, v38, v170
	global_store_dword v138, v24, s[16:17]
	s_waitcnt vmcnt(31)
	v_fma_f32 v25, v25, v38, v171
	global_store_dword v139, v25, s[16:17]
	s_waitcnt vmcnt(31)
	v_fma_f32 v26, v26, v38, v172
	global_store_dword v140, v26, s[16:17]
	s_waitcnt vmcnt(31)
	v_fma_f32 v27, v27, v38, v173
	global_store_dword v141, v27, s[16:17]
	s_waitcnt vmcnt(31)
	v_fma_f32 v28, v28, v38, v174
	global_store_dword v142, v28, s[16:17]
	s_waitcnt vmcnt(31)
	v_fma_f32 v29, v29, v38, v175
	global_store_dword v143, v29, s[16:17]
	s_waitcnt vmcnt(31)
	v_fma_f32 v30, v30, v38, v176
	global_store_dword v144, v30, s[16:17]
	s_waitcnt vmcnt(31)
	v_fma_f32 v31, v31, v38, v177
	global_store_dword v145, v31, s[16:17]
	s_waitcnt vmcnt(31)
	v_fma_f32 v32, v32, v38, v178
	global_store_dword v146, v32, s[16:17]
	s_waitcnt vmcnt(31)
	v_fma_f32 v33, v33, v38, v179
	global_store_dword v147, v33, s[16:17]
	s_waitcnt vmcnt(31)
	v_fma_f32 v2, v2, v38, v180
	global_store_dword v148, v2, s[16:17]
	s_waitcnt vmcnt(31)
	v_fma_f32 v3, v3, v38, v181
	global_store_dword v149, v3, s[16:17]
	s_waitcnt vmcnt(31)
	v_fma_f32 v4, v4, v38, v182
	global_store_dword v150, v4, s[16:17]
	s_waitcnt vmcnt(31)
	v_fma_f32 v5, v5, v38, v183
	global_store_dword v151, v5, s[16:17]
	s_waitcnt vmcnt(31)
	v_fma_f32 v6, v6, v38, v184
	global_store_dword v152, v6, s[16:17]
	s_waitcnt vmcnt(31)
	v_fma_f32 v7, v7, v38, v185
	global_store_dword v153, v7, s[16:17]
	s_waitcnt vmcnt(31)
	v_fma_f32 v8, v8, v38, v186
	global_store_dword v154, v8, s[16:17]
	s_waitcnt vmcnt(31)
	v_fma_f32 v9, v9, v38, v187
	global_store_dword v155, v9, s[16:17]
	s_waitcnt vmcnt(31)
	v_fma_f32 v10, v10, v38, v188
	global_store_dword v156, v10, s[16:17]
	s_waitcnt vmcnt(31)
	v_fma_f32 v11, v11, v38, v189
	global_store_dword v157, v11, s[16:17]
	s_waitcnt vmcnt(31)
	v_fma_f32 v12, v12, v38, v190
	global_store_dword v158, v12, s[16:17]
	s_waitcnt vmcnt(31)
	v_fma_f32 v13, v13, v38, v191
	global_store_dword v159, v13, s[16:17]
	s_waitcnt vmcnt(31)
	v_fma_f32 v14, v14, v38, v192
	global_store_dword v160, v14, s[16:17]
	s_waitcnt vmcnt(31)
	v_fma_f32 v15, v15, v38, v193
	global_store_dword v161, v15, s[16:17]
	s_waitcnt vmcnt(31)
	v_fma_f32 v16, v16, v38, v194
	global_store_dword v162, v16, s[16:17]
	s_waitcnt vmcnt(31)
	v_fma_f32 v17, v17, v38, v195
	global_store_dword v163, v17, s[16:17]
	s_branch .LBB0_1785

; DI int crow(int r, int hh) { return (r & 3) + 8 * (r >> 2) + 4 * hh; }
; DI void resid_ctx_half(KP p, int l, int u, int which, const u16* A, int K, const u16* Wt, const float* xin, float* xout, char* smem) {
;     ...
;   const float* gate = (const float*)(p->ws + OFF_MODS) + (size_t)(l * 5 + 4) * 6144 + which * 3072 + 2048;
; #pragma unroll
;   for (int i = 0; i < 2; ++i) {
;     const int mrow0 = (mt - 128) * 128 + wm * 64 + i * 32, n = nt * 64 + wn * 32 + l31;
;     const float gv = gate[n];
; #pragma unroll
;     for (int r = 0; r < 16; ++r) {
;       const size_t o = (size_t)(mrow0 + crow(r, hh)) * 1024 + n;
;       xout[o] = xin[o] + gv * acc[i][0][r];
;     }
;   }
.LBB0_2015:
	s_load_dwordx2 s[4:5], s[12:13], 0x130
	s_waitcnt vmcnt(5)
	v_lshrrev_b32_e32 v36, 1, v63
	s_add_u32 s10, s8, 0xe420000
	v_and_b32_e32 v34, 31, v62
	v_and_b32_e32 v36, 32, v36
	s_addc_u32 s11, s9, 0
	v_or3_b32 v34, v34, v36, s3
	s_add_u32 s8, s14, 0xe420000
	v_ashrrev_i32_e32 v35, 1, v63
	v_lshlrev_b32_e32 v198, 2, v34
	v_lshrrev_b32_e32 v34, 3, v62
	s_addc_u32 s9, s15, 0
	v_and_b32_e32 v35, 0xffffffc0, v35
	v_and_or_b32 v34, v34, 4, s2
	s_waitcnt lgkmcnt(0)
	s_add_u32 s4, s4, s6
	v_add_u32_e32 v34, v34, v35
	s_addc_u32 s5, s5, s7
	v_ashrrev_i32_e32 v35, 31, v34
	v_lshl_add_u64 v[36:37], s[4:5], 0, v[198:199]
	s_mov_b32 s2, 0xe83d000
	s_waitcnt vmcnt(4)
	v_lshlrev_b64 v[40:41], 12, v[34:35]
	v_add_co_u32_e32 v36, vcc, s2, v36
	v_or_b32_e32 v40, v40, v198
	s_nop 0
	v_addc_co_u32_e32 v37, vcc, 0, v37, vcc
	global_load_dword v38, v[36:37], off
	v_lshl_or_b32 v196, v34, 12, v198
	v_mov_b32_e32 v132, v196
	v_add_u32_e32 v133, 0x1000, v196
	v_add_u32_e32 v134, 0x2000, v196
	v_add_u32_e32 v135, 0x3000, v196
	v_add_u32_e32 v136, 0x8000, v196
	v_add_u32_e32 v137, 0x9000, v196
	v_add_u32_e32 v138, 0xa000, v196
	v_add_u32_e32 v139, 0xb000, v196
	v_add_u32_e32 v140, 0x10000, v196
	v_add_u32_e32 v141, 0x11000, v196
	v_add_u32_e32 v142, 0x12000, v196
	v_add_u32_e32 v143, 0x13000, v196
	v_add_u32_e32 v144, 0x18000, v196
	v_add_u32_e32 v145, 0x19000, v196
	v_add_u32_e32 v146, 0x1a000, v196
	v_add_u32_e32 v147, 0x1b000, v196
	v_add_u32_e32 v148, 0x20000, v196
	v_add_u32_e32 v149, 0x21000, v196
	v_add_u32_e32 v150, 0x22000, v196
	v_add_u32_e32 v151, 0x23000, v196
	v_add_u32_e32 v152, 0x28000, v196
	v_add_u32_e32 v153, 0x29000, v196
	v_add_u32_e32 v154, 0x2a000, v196
	v_add_u32_e32 v155, 0x2b000, v196
	v_add_u32_e32 v156, 0x30000, v196
	v_add_u32_e32 v157, 0x31000, v196
	v_add_u32_e32 v158, 0x32000, v196
	v_add_u32_e32 v159, 0x33000, v196
	v_add_u32_e32 v160, 0x38000, v196
	v_add_u32_e32 v161, 0x39000, v196
	v_add_u32_e32 v162, 0x3a000, v196
	v_add_u32_e32 v163, 0x3b000, v196
	global_load_dword v164, v132, s[10:11]
	global_load_dword v165, v133, s[10:11]
	global_load_dword v166, v134, s[10:11]
	global_load_dword v167, v135, s[10:11]
	global_load_dword v168, v136, s[10:11]
	global_load_dword v169, v137, s[10:11]
	global_load_dword v170, v138, s[10:11]
	global_load_dword v171, v139, s[10:11]
	global_load_dword v172, v140, s[10:11]
	global_load_dword v173, v141, s[10:11]
	global_load_dword v174, v142, s[10:11]
	global_load_dword v175, v143, s[10:11]
	global_load_dword v176, v144, s[10:11]
	global_load_dword v177, v145, s[10:11]
	global_load_dword v178, v146, s[10:11]
	global_load_dword v179, v147, s[10:11]
	global_load_dword v180, v148, s[10:11]
	global_load_dword v181, v149, s[10:11]
	global_load_dword v182, v150, s[10:11]
	global_load_dword v183, v151, s[10:11]
	global_load_dword v184, v152, s[10:11]
	global_load_dword v185, v153, s[10:11]
	global_load_dword v186, v154, s[10:11]
	global_load_dword v187, v155, s[10:11]
	global_load_dword v188, v156, s[10:11]
	global_load_dword v189, v157, s[10:11]
	global_load_dword v190, v158, s[10:11]
	global_load_dword v191, v159, s[10:11]
	global_load_dword v192, v160, s[10:11]
	global_load_dword v193, v161, s[10:11]
	global_load_dword v194, v162, s[10:11]
	global_load_dword v195, v163, s[10:11]
	s_waitcnt vmcnt(31)
	v_fma_f32 v18, v18, v38, v164
	global_store_dword v132, v18, s[8:9]
	s_waitcnt vmcnt(31)
	v_fma_f32 v19, v19, v38, v165
	global_store_dword v133, v19, s[8:9]
	s_waitcnt vmcnt(31)
	v_fma_f32 v20, v20, v38, v166
	global_store_dword v134, v20, s[8:9]
	s_waitcnt vmcnt(31)
	v_fma_f32 v21, v21, v38, v167
	global_store_dword v135, v21, s[8:9]
	s_waitcnt vmcnt(31)
	v_fma_f32 v22, v22, v38, v168
	global_store_dword v136, v22, s[8:9]
	s_waitcnt vmcnt(31)
	v_fma_f32 v23, v23, v38, v169
	global_store_dword v137, v23, s[8:9]
	s_waitcnt vmcnt(31)
	v_fma_f32 v24, v24, v38, v170
	global_store_dword v138, v24, s[8:9]
	s_waitcnt vmcnt(31)
	v_fma_f32 v25, v25, v38, v171
	global_store_dword v139, v25, s[8:9]
	s_waitcnt vmcnt(31)
	v_fma_f32 v26, v26, v38, v172
	global_store_dword v140, v26, s[8:9]
	s_waitcnt vmcnt(31)
	v_fma_f32 v27, v27, v38, v173
	global_store_dword v141, v27, s[8:9]
	s_waitcnt vmcnt(31)
	v_fma_f32 v28, v28, v38, v174
	global_store_dword v142, v28, s[8:9]
	s_waitcnt vmcnt(31)
	v_fma_f32 v29, v29, v38, v175
	global_store_dword v143, v29, s[8:9]
	s_waitcnt vmcnt(31)
	v_fma_f32 v30, v30, v38, v176
	global_store_dword v144, v30, s[8:9]
	s_waitcnt vmcnt(31)
	v_fma_f32 v31, v31, v38, v177
	global_store_dword v145, v31, s[8:9]
	s_waitcnt vmcnt(31)
	v_fma_f32 v32, v32, v38, v178
	global_store_dword v146, v32, s[8:9]
	s_waitcnt vmcnt(31)
	v_fma_f32 v33, v33, v38, v179
	global_store_dword v147, v33, s[8:9]
	s_waitcnt vmcnt(31)
	v_fma_f32 v2, v2, v38, v180
	global_store_dword v148, v2, s[8:9]
	s_waitcnt vmcnt(31)
	v_fma_f32 v3, v3, v38, v181
	global_store_dword v149, v3, s[8:9]
	s_waitcnt vmcnt(31)
	v_fma_f32 v4, v4, v38, v182
	global_store_dword v150, v4, s[8:9]
	s_waitcnt vmcnt(31)
	v_fma_f32 v5, v5, v38, v183
	global_store_dword v151, v5, s[8:9]
	s_waitcnt vmcnt(31)
	v_fma_f32 v6, v6, v38, v184
	global_store_dword v152, v6, s[8:9]
	s_waitcnt vmcnt(31)
	v_fma_f32 v7, v7, v38, v185
	global_store_dword v153, v7, s[8:9]
	s_waitcnt vmcnt(31)
	v_fma_f32 v8, v8, v38, v186
	global_store_dword v154, v8, s[8:9]
	s_waitcnt vmcnt(31)
	v_fma_f32 v9, v9, v38, v187
	global_store_dword v155, v9, s[8:9]
	s_waitcnt vmcnt(31)
	v_fma_f32 v10, v10, v38, v188
	global_store_dword v156, v10, s[8:9]
	s_waitcnt vmcnt(31)
	v_fma_f32 v11, v11, v38, v189
	global_store_dword v157, v11, s[8:9]
	s_waitcnt vmcnt(31)
	v_fma_f32 v12, v12, v38, v190
	global_store_dword v158, v12, s[8:9]
	s_waitcnt vmcnt(31)
	v_fma_f32 v13, v13, v38, v191
	global_store_dword v159, v13, s[8:9]
	s_waitcnt vmcnt(31)
	v_fma_f32 v14, v14, v38, v192
	global_store_dword v160, v14, s[8:9]
	s_waitcnt vmcnt(31)
	v_fma_f32 v15, v15, v38, v193
	global_store_dword v161, v15, s[8:9]
	s_waitcnt vmcnt(31)
	v_fma_f32 v16, v16, v38, v194
	global_store_dword v162, v16, s[8:9]
	s_waitcnt vmcnt(31)
	v_fma_f32 v17, v17, v38, v195
	global_store_dword v163, v17, s[8:9]
	s_mov_b64 s[8:9], 0
